# K loops (P1,P4,P5) loop head: next-tile pointer select SALU run sunk below phase 1's LDS reads and LDS-DMA loads so they issue first
# baseline (speedup 1.0000x reference)
.LBB0_118:
	ds_read_b128 v[128:131], v221
	ds_read_b128 v[132:135], v221 offset:1024
	ds_read_b128 v[136:139], v221 offset:2048
	ds_read_b128 v[140:143], v221 offset:3072


	s_add_i32 m0, s58, 0xc000
	ds_read_b128 v[144:147], v222
	ds_read_b128 v[148:151], v222 offset:1024
	ds_read_b128 v[152:155], v222 offset:2048
	ds_read_b128 v[156:159], v222 offset:3072
	ds_read_b128 v[160:163], v222 offset:4096
	ds_read_b128 v[164:167], v222 offset:5120
	ds_read_b128 v[190:193], v222 offset:6144
	ds_read_b128 v[194:197], v222 offset:7168
	global_load_lds_dwordx4 v182, s[6:7]
	s_add_i32 m0, s58, 0xe000
	s_nop 0

	global_load_lds_dwordx4 v184, s[6:7]
	s_add_u32 s8, s6, 0xfff80080
	s_addc_u32 s9, s7, -1
	s_cmp_eq_u32 s53, 28
	s_cselect_b32 s11, s5, s9
	s_cselect_b32 s10, s33, s8
	s_cselect_b32 s9, s43, s52
	s_cselect_b32 s8, s45, s51
	s_waitcnt lgkmcnt(8)
	s_barrier
	s_waitcnt lgkmcnt(0)


	v_mfma_f32_16x16x32_bf16 v[124:127], v[128:131], v[144:147], v[124:127]
	v_mfma_f32_16x16x32_bf16 v[116:119], v[136:139], v[144:147], v[116:119]
	v_mfma_f32_16x16x32_bf16 v[108:111], v[128:131], v[152:155], v[108:111]
	v_mfma_f32_16x16x32_bf16 v[100:103], v[136:139], v[152:155], v[100:103]
	v_mfma_f32_16x16x32_bf16 v[92:95], v[128:131], v[160:163], v[92:95]
	v_mfma_f32_16x16x32_bf16 v[84:87], v[136:139], v[160:163], v[84:87]
	v_mfma_f32_16x16x32_bf16 v[76:79], v[128:131], v[190:193], v[76:79]
	v_mfma_f32_16x16x32_bf16 v[68:71], v[136:139], v[190:193], v[68:71]
	v_mfma_f32_16x16x32_bf16 v[124:127], v[132:135], v[148:151], v[124:127]
	v_mfma_f32_16x16x32_bf16 v[116:119], v[140:143], v[148:151], v[116:119]
	v_mfma_f32_16x16x32_bf16 v[108:111], v[132:135], v[156:159], v[108:111]
	v_mfma_f32_16x16x32_bf16 v[100:103], v[140:143], v[156:159], v[100:103]
	v_mfma_f32_16x16x32_bf16 v[92:95], v[132:135], v[164:167], v[92:95]
	v_mfma_f32_16x16x32_bf16 v[84:87], v[140:143], v[164:167], v[84:87]
	v_mfma_f32_16x16x32_bf16 v[76:79], v[132:135], v[194:197], v[76:79]
	v_mfma_f32_16x16x32_bf16 v[68:71], v[140:143], v[194:197], v[68:71]

	s_barrier
	s_add_i32 s54, s81, s57
	s_add_u32 s66, s8, s20
	s_addc_u32 s67, s9, s21
	s_mov_b32 m0, s54
	ds_read_b128 v[198:201], v223
	ds_read_b128 v[202:205], v223 offset:1024
	ds_read_b128 v[206:209], v223 offset:2048
	ds_read_b128 v[226:229], v223 offset:3072
	global_load_lds_dwordx4 v172, s[8:9]
	s_add_i32 m0, s54, 0x2000
	s_nop 0

	global_load_lds_dwordx4 v174, s[8:9]
	s_barrier
	s_waitcnt lgkmcnt(0)


	v_mfma_f32_16x16x32_bf16 v[120:123], v[198:201], v[144:147], v[120:123]
	v_mfma_f32_16x16x32_bf16 v[112:115], v[206:209], v[144:147], v[112:115]
	v_mfma_f32_16x16x32_bf16 v[104:107], v[198:201], v[152:155], v[104:107]
	v_mfma_f32_16x16x32_bf16 v[96:99], v[206:209], v[152:155], v[96:99]
	v_mfma_f32_16x16x32_bf16 v[88:91], v[198:201], v[160:163], v[88:91]
	v_mfma_f32_16x16x32_bf16 v[80:83], v[206:209], v[160:163], v[80:83]
	v_mfma_f32_16x16x32_bf16 v[72:75], v[198:201], v[190:193], v[72:75]
	v_mfma_f32_16x16x32_bf16 v[64:67], v[206:209], v[190:193], v[64:67]
	v_mfma_f32_16x16x32_bf16 v[120:123], v[202:205], v[148:151], v[120:123]
	v_mfma_f32_16x16x32_bf16 v[112:115], v[226:229], v[148:151], v[112:115]
	v_mfma_f32_16x16x32_bf16 v[104:107], v[202:205], v[156:159], v[104:107]
	v_mfma_f32_16x16x32_bf16 v[96:99], v[226:229], v[156:159], v[96:99]
	v_mfma_f32_16x16x32_bf16 v[88:91], v[202:205], v[164:167], v[88:91]
	v_mfma_f32_16x16x32_bf16 v[80:83], v[226:229], v[164:167], v[80:83]
	v_mfma_f32_16x16x32_bf16 v[72:75], v[202:205], v[194:197], v[72:75]
	v_mfma_f32_16x16x32_bf16 v[64:67], v[226:229], v[194:197], v[64:67]

	s_mov_b32 m0, s58
	s_add_u32 s68, s10, s20
	s_addc_u32 s69, s11, s21
	s_barrier
	ds_read_b128 v[144:147], v222 offset:16384
	ds_read_b128 v[148:151], v222 offset:17408
	ds_read_b128 v[152:155], v222 offset:18432
	ds_read_b128 v[156:159], v222 offset:19456
	ds_read_b128 v[160:163], v222 offset:20480
	ds_read_b128 v[164:167], v222 offset:21504
	ds_read_b128 v[190:193], v222 offset:22528
	ds_read_b128 v[194:197], v222 offset:23552
	global_load_lds_dwordx4 v172, s[10:11]
	s_mov_b32 m0, s59
	s_nop 0

	global_load_lds_dwordx4 v174, s[10:11]
	s_barrier
	s_waitcnt lgkmcnt(0)


	v_mfma_f32_16x16x32_bf16 v[60:63], v[128:131], v[144:147], v[60:63]
	v_mfma_f32_16x16x32_bf16 v[52:55], v[136:139], v[144:147], v[52:55]
	v_mfma_f32_16x16x32_bf16 v[44:47], v[128:131], v[152:155], v[44:47]
	v_mfma_f32_16x16x32_bf16 v[36:39], v[136:139], v[152:155], v[36:39]
	v_mfma_f32_16x16x32_bf16 v[28:31], v[128:131], v[160:163], v[28:31]
	v_mfma_f32_16x16x32_bf16 v[20:23], v[136:139], v[160:163], v[20:23]
	v_mfma_f32_16x16x32_bf16 v[12:15], v[128:131], v[190:193], v[12:15]
	v_mfma_f32_16x16x32_bf16 v[4:7], v[136:139], v[190:193], v[4:7]
	v_mfma_f32_16x16x32_bf16 v[60:63], v[132:135], v[148:151], v[60:63]
	v_mfma_f32_16x16x32_bf16 v[52:55], v[140:143], v[148:151], v[52:55]
	v_mfma_f32_16x16x32_bf16 v[44:47], v[132:135], v[156:159], v[44:47]
	v_mfma_f32_16x16x32_bf16 v[36:39], v[140:143], v[156:159], v[36:39]
	v_mfma_f32_16x16x32_bf16 v[28:31], v[132:135], v[164:167], v[28:31]
	v_mfma_f32_16x16x32_bf16 v[20:23], v[140:143], v[164:167], v[20:23]
	v_mfma_f32_16x16x32_bf16 v[12:15], v[132:135], v[194:197], v[12:15]
	v_mfma_f32_16x16x32_bf16 v[4:7], v[140:143], v[194:197], v[4:7]

	s_barrier
	s_add_u32 s54, s8, 0x80000
	s_addc_u32 s55, s9, 0
	s_add_i32 vcc_lo, s30, s57
	s_mov_b32 m0, vcc_lo
	s_nop 0

	global_load_lds_dwordx4 v172, s[54:55]
	s_add_i32 m0, vcc_lo, 0x2000
	s_nop 0

	global_load_lds_dwordx4 v174, s[54:55]
	s_waitcnt vmcnt(6)
	s_barrier

	v_mfma_f32_16x16x32_bf16 v[56:59], v[198:201], v[144:147], v[56:59]
	v_mfma_f32_16x16x32_bf16 v[48:51], v[206:209], v[144:147], v[48:51]
	v_mfma_f32_16x16x32_bf16 v[40:43], v[198:201], v[152:155], v[40:43]
	v_mfma_f32_16x16x32_bf16 v[32:35], v[206:209], v[152:155], v[32:35]
	v_mfma_f32_16x16x32_bf16 v[24:27], v[198:201], v[160:163], v[24:27]
	v_mfma_f32_16x16x32_bf16 v[16:19], v[206:209], v[160:163], v[16:19]
	v_mfma_f32_16x16x32_bf16 v[8:11], v[198:201], v[190:193], v[8:11]
	v_mfma_f32_16x16x32_bf16 v[0:3], v[206:209], v[190:193], v[0:3]
	v_mfma_f32_16x16x32_bf16 v[56:59], v[202:205], v[148:151], v[56:59]
	v_mfma_f32_16x16x32_bf16 v[48:51], v[226:229], v[148:151], v[48:51]
	v_mfma_f32_16x16x32_bf16 v[40:43], v[202:205], v[156:159], v[40:43]
	v_mfma_f32_16x16x32_bf16 v[32:35], v[226:229], v[156:159], v[32:35]
	v_mfma_f32_16x16x32_bf16 v[24:27], v[202:205], v[164:167], v[24:27]
	v_mfma_f32_16x16x32_bf16 v[16:19], v[226:229], v[164:167], v[16:19]
	v_mfma_f32_16x16x32_bf16 v[8:11], v[202:205], v[194:197], v[8:11]
	v_mfma_f32_16x16x32_bf16 v[0:3], v[226:229], v[194:197], v[0:3]

	s_add_i32 s54, 0, 0x18000

	s_barrier
	ds_read_b128 v[128:131], v221 offset:32768
	ds_read_b128 v[132:135], v221 offset:33792
	ds_read_b128 v[136:139], v221 offset:34816
	ds_read_b128 v[140:143], v221 offset:35840
	s_add_u32 s10, s10, 0x80000
	s_addc_u32 s11, s11, 0
	s_mov_b32 m0, s2

	ds_read_b128 v[144:147], v222 offset:32768
	ds_read_b128 v[148:151], v222 offset:33792
	ds_read_b128 v[152:155], v222 offset:34816
	ds_read_b128 v[156:159], v222 offset:35840
	ds_read_b128 v[160:163], v222 offset:36864
	ds_read_b128 v[164:167], v222 offset:37888
	ds_read_b128 v[190:193], v222 offset:38912
	ds_read_b128 v[194:197], v222 offset:39936
	global_load_lds_dwordx4 v172, s[10:11]
	s_mov_b32 m0, s3
	s_nop 0

	global_load_lds_dwordx4 v174, s[10:11]
	s_waitcnt lgkmcnt(8)
	s_barrier
	s_waitcnt lgkmcnt(0)


	v_mfma_f32_16x16x32_bf16 v[124:127], v[128:131], v[144:147], v[124:127]
	v_mfma_f32_16x16x32_bf16 v[116:119], v[136:139], v[144:147], v[116:119]
	v_mfma_f32_16x16x32_bf16 v[108:111], v[128:131], v[152:155], v[108:111]
	v_mfma_f32_16x16x32_bf16 v[100:103], v[136:139], v[152:155], v[100:103]
	v_mfma_f32_16x16x32_bf16 v[92:95], v[128:131], v[160:163], v[92:95]
	v_mfma_f32_16x16x32_bf16 v[84:87], v[136:139], v[160:163], v[84:87]
	v_mfma_f32_16x16x32_bf16 v[76:79], v[128:131], v[190:193], v[76:79]
	v_mfma_f32_16x16x32_bf16 v[68:71], v[136:139], v[190:193], v[68:71]
	v_mfma_f32_16x16x32_bf16 v[124:127], v[132:135], v[148:151], v[124:127]
	v_mfma_f32_16x16x32_bf16 v[116:119], v[140:143], v[148:151], v[116:119]
	v_mfma_f32_16x16x32_bf16 v[108:111], v[132:135], v[156:159], v[108:111]
	v_mfma_f32_16x16x32_bf16 v[100:103], v[140:143], v[156:159], v[100:103]
	v_mfma_f32_16x16x32_bf16 v[92:95], v[132:135], v[164:167], v[92:95]
	v_mfma_f32_16x16x32_bf16 v[84:87], v[140:143], v[164:167], v[84:87]
	v_mfma_f32_16x16x32_bf16 v[76:79], v[132:135], v[194:197], v[76:79]
	v_mfma_f32_16x16x32_bf16 v[68:71], v[140:143], v[194:197], v[68:71]

	s_barrier
	s_add_i32 s10, 0, 0x1c000
	s_add_i32 s11, s54, s57


	s_mov_b32 m0, s11
	ds_read_b128 v[198:201], v223 offset:32768
	ds_read_b128 v[202:205], v223 offset:33792
	ds_read_b128 v[206:209], v223 offset:34816
	ds_read_b128 v[226:229], v223 offset:35840
	global_load_lds_dwordx4 v172, s[66:67]
	s_add_i32 m0, s11, 0x2000
	s_nop 0

	global_load_lds_dwordx4 v174, s[66:67]
	s_barrier
	s_waitcnt lgkmcnt(0)


	v_mfma_f32_16x16x32_bf16 v[120:123], v[198:201], v[144:147], v[120:123]
	v_mfma_f32_16x16x32_bf16 v[112:115], v[206:209], v[144:147], v[112:115]
	v_mfma_f32_16x16x32_bf16 v[104:107], v[198:201], v[152:155], v[104:107]
	v_mfma_f32_16x16x32_bf16 v[96:99], v[206:209], v[152:155], v[96:99]
	v_mfma_f32_16x16x32_bf16 v[88:91], v[198:201], v[160:163], v[88:91]
	v_mfma_f32_16x16x32_bf16 v[80:83], v[206:209], v[160:163], v[80:83]
	v_mfma_f32_16x16x32_bf16 v[72:75], v[198:201], v[190:193], v[72:75]
	v_mfma_f32_16x16x32_bf16 v[64:67], v[206:209], v[190:193], v[64:67]
	v_mfma_f32_16x16x32_bf16 v[120:123], v[202:205], v[148:151], v[120:123]
	v_mfma_f32_16x16x32_bf16 v[112:115], v[226:229], v[148:151], v[112:115]
	v_mfma_f32_16x16x32_bf16 v[104:107], v[202:205], v[156:159], v[104:107]
	v_mfma_f32_16x16x32_bf16 v[96:99], v[226:229], v[156:159], v[96:99]
	v_mfma_f32_16x16x32_bf16 v[88:91], v[202:205], v[164:167], v[88:91]
	v_mfma_f32_16x16x32_bf16 v[80:83], v[226:229], v[164:167], v[80:83]
	v_mfma_f32_16x16x32_bf16 v[72:75], v[202:205], v[194:197], v[72:75]
	v_mfma_f32_16x16x32_bf16 v[64:67], v[226:229], v[194:197], v[64:67]

	s_mov_b32 m0, s96

	s_barrier
	ds_read_b128 v[144:147], v222 offset:49152
	ds_read_b128 v[148:151], v222 offset:50176
	ds_read_b128 v[152:155], v222 offset:51200
	ds_read_b128 v[156:159], v222 offset:52224
	ds_read_b128 v[160:163], v222 offset:53248
	ds_read_b128 v[164:167], v222 offset:54272
	ds_read_b128 v[190:193], v222 offset:55296
	ds_read_b128 v[194:197], v222 offset:56320
	global_load_lds_dwordx4 v172, s[68:69]
	s_mov_b32 m0, s97
	s_nop 0

	global_load_lds_dwordx4 v174, s[68:69]
	s_barrier
	s_waitcnt lgkmcnt(0)


	v_mfma_f32_16x16x32_bf16 v[60:63], v[128:131], v[144:147], v[60:63]
	v_mfma_f32_16x16x32_bf16 v[52:55], v[136:139], v[144:147], v[52:55]
	v_mfma_f32_16x16x32_bf16 v[44:47], v[128:131], v[152:155], v[44:47]
	v_mfma_f32_16x16x32_bf16 v[36:39], v[136:139], v[152:155], v[36:39]
	v_mfma_f32_16x16x32_bf16 v[28:31], v[128:131], v[160:163], v[28:31]
	v_mfma_f32_16x16x32_bf16 v[20:23], v[136:139], v[160:163], v[20:23]
	v_mfma_f32_16x16x32_bf16 v[12:15], v[128:131], v[190:193], v[12:15]
	v_mfma_f32_16x16x32_bf16 v[4:7], v[136:139], v[190:193], v[4:7]
	v_mfma_f32_16x16x32_bf16 v[60:63], v[132:135], v[148:151], v[60:63]
	v_mfma_f32_16x16x32_bf16 v[52:55], v[140:143], v[148:151], v[52:55]
	v_mfma_f32_16x16x32_bf16 v[44:47], v[132:135], v[156:159], v[44:47]
	v_mfma_f32_16x16x32_bf16 v[36:39], v[140:143], v[156:159], v[36:39]
	v_mfma_f32_16x16x32_bf16 v[28:31], v[132:135], v[164:167], v[28:31]
	v_mfma_f32_16x16x32_bf16 v[20:23], v[140:143], v[164:167], v[20:23]
	v_mfma_f32_16x16x32_bf16 v[12:15], v[132:135], v[194:197], v[12:15]
	v_mfma_f32_16x16x32_bf16 v[4:7], v[140:143], v[194:197], v[4:7]

	s_barrier
	s_add_u32 s8, s8, 0x80080
	s_addc_u32 s9, s9, 0
	s_add_i32 s10, s10, s57
	s_mov_b32 m0, s10
	s_add_i32 s53, s53, 2

	global_load_lds_dwordx4 v172, s[8:9]
	s_add_i32 m0, s10, 0x2000
	s_add_u32 s6, s6, 0x100
	s_addc_u32 s7, s7, 0

	global_load_lds_dwordx4 v174, s[8:9]
	s_add_u32 s51, s51, 0x100
	s_addc_u32 s52, s52, 0
	s_waitcnt vmcnt(6)
	s_barrier

	v_mfma_f32_16x16x32_bf16 v[56:59], v[198:201], v[144:147], v[56:59]
	v_mfma_f32_16x16x32_bf16 v[48:51], v[206:209], v[144:147], v[48:51]
	v_mfma_f32_16x16x32_bf16 v[40:43], v[198:201], v[152:155], v[40:43]
	v_mfma_f32_16x16x32_bf16 v[32:35], v[206:209], v[152:155], v[32:35]
	v_mfma_f32_16x16x32_bf16 v[24:27], v[198:201], v[160:163], v[24:27]
	v_mfma_f32_16x16x32_bf16 v[16:19], v[206:209], v[160:163], v[16:19]
	v_mfma_f32_16x16x32_bf16 v[8:11], v[198:201], v[190:193], v[8:11]
	v_mfma_f32_16x16x32_bf16 v[0:3], v[206:209], v[190:193], v[0:3]
	v_mfma_f32_16x16x32_bf16 v[56:59], v[202:205], v[148:151], v[56:59]
	v_mfma_f32_16x16x32_bf16 v[48:51], v[226:229], v[148:151], v[48:51]
	v_mfma_f32_16x16x32_bf16 v[40:43], v[202:205], v[156:159], v[40:43]
	v_mfma_f32_16x16x32_bf16 v[32:35], v[226:229], v[156:159], v[32:35]
	v_mfma_f32_16x16x32_bf16 v[24:27], v[202:205], v[164:167], v[24:27]
	v_mfma_f32_16x16x32_bf16 v[16:19], v[226:229], v[164:167], v[16:19]
	v_mfma_f32_16x16x32_bf16 v[8:11], v[202:205], v[194:197], v[8:11]
	v_mfma_f32_16x16x32_bf16 v[0:3], v[226:229], v[194:197], v[0:3]


	s_cmp_gt_u32 s53, 29
	s_barrier
	s_cbranch_scc0 .LBB0_118
	v_mov_b32_e32 v142, v210
	v_mov_b32_e32 v143, v169
	s_lshl_b32 s33, s4, 8
	s_add_i32 s33, s33, s34
	v_lshl_add_u32 v133, v142, 4, v143
	v_ashrrev_i32_e32 v198, 2, v133
	v_and_b32_e32 v192, 3, v143
	v_and_b32_e32 v128, -4, v133
	s_cmp_gt_i32 s4, 30
	v_lshl_add_u32 v226, v192, 6, v128
	v_add_u32_e32 v190, s33, v198
	s_cselect_b64 s[52:53], -1, 0
	s_cmp_gt_i32 s50, 8
	s_mov_b64 s[4:5], -1
	s_cbranch_scc0 .LBB0_419
	s_cmp_lg_u32 s50, 9
	s_cbranch_scc0 .LBB0_225
	s_cmp_gt_u32 s50, 25
	s_cbranch_scc0 .LBB0_127
	v_mul_f32_e32 v130, 0xbfb8aa3b, v120
	v_mul_f32_e32 v131, 0xbfb8aa3b, v121
	v_mul_f32_e32 v132, 0xbfb8aa3b, v122
	v_mul_f32_e32 v134, 0xbfb8aa3b, v123
	v_mul_f32_e32 v135, 0xbfb8aa3b, v112
	v_mul_f32_e32 v136, 0xbfb8aa3b, v113
	v_mul_f32_e32 v137, 0xbfb8aa3b, v114
	v_mul_f32_e32 v138, 0xbfb8aa3b, v115
	v_mul_f32_e32 v139, 0xbfb8aa3b, v104
	v_mul_f32_e32 v140, 0xbfb8aa3b, v105
	v_mul_f32_e32 v141, 0xbfb8aa3b, v106
	v_mul_f32_e32 v144, 0xbfb8aa3b, v107
	v_mul_f32_e32 v145, 0xbfb8aa3b, v96
	v_mul_f32_e32 v146, 0xbfb8aa3b, v97
	v_mul_f32_e32 v147, 0xbfb8aa3b, v98
	v_mul_f32_e32 v148, 0xbfb8aa3b, v99
	v_mul_f32_e32 v149, 0xbfb8aa3b, v88
	v_mul_f32_e32 v150, 0xbfb8aa3b, v89
	v_mul_f32_e32 v151, 0xbfb8aa3b, v90
	v_mul_f32_e32 v152, 0xbfb8aa3b, v91
	v_mul_f32_e32 v153, 0xbfb8aa3b, v80
	v_mul_f32_e32 v154, 0xbfb8aa3b, v81
	v_mul_f32_e32 v155, 0xbfb8aa3b, v82
	v_mul_f32_e32 v180, 0xbfb8aa3b, v83
	v_mul_f32_e32 v206, 0xbfb8aa3b, v72
	v_mul_f32_e32 v207, 0xbfb8aa3b, v73
	v_mul_f32_e32 v208, 0xbfb8aa3b, v74
	v_mul_f32_e32 v209, 0xbfb8aa3b, v75
	v_mul_f32_e32 v227, 0xbfb8aa3b, v64
	v_mul_f32_e32 v228, 0xbfb8aa3b, v65
	v_mul_f32_e32 v229, 0xbfb8aa3b, v66
	v_mul_f32_e32 v230, 0xbfb8aa3b, v67
	v_exp_f32_e32 v205, v130
	v_exp_f32_e32 v204, v131
	v_exp_f32_e32 v203, v132
	v_exp_f32_e32 v202, v134
	v_exp_f32_e32 v200, v135
	v_exp_f32_e32 v199, v136
	v_exp_f32_e32 v197, v137
	v_exp_f32_e32 v196, v138
	v_exp_f32_e32 v195, v139
	v_exp_f32_e32 v194, v140
	v_exp_f32_e32 v193, v141
	v_exp_f32_e32 v167, v144
	v_exp_f32_e32 v166, v145
	v_exp_f32_e32 v165, v146
	v_exp_f32_e32 v164, v147
	v_exp_f32_e32 v163, v148
	v_exp_f32_e32 v162, v149
	v_exp_f32_e32 v161, v150
	v_exp_f32_e32 v160, v151
	v_exp_f32_e32 v159, v152
	v_exp_f32_e32 v158, v153
	v_exp_f32_e32 v157, v154
	v_exp_f32_e32 v156, v155
	v_exp_f32_e32 v155, v180
	v_exp_f32_e32 v154, v206
	v_exp_f32_e32 v153, v207
	v_exp_f32_e32 v152, v208
	v_exp_f32_e32 v151, v209
	v_exp_f32_e32 v150, v227
	v_exp_f32_e32 v149, v228
	v_exp_f32_e32 v148, v229
	v_exp_f32_e32 v147, v230
	v_ashrrev_i32_e32 v191, 31, v190
	s_cmp_lt_u32 s50, 42
	v_lshlrev_b32_e32 v201, 2, v192
	v_lshlrev_b64 v[128:129], 12, v[190:191]
	v_mul_f32_e32 v146, 0xbfb8aa3b, v56
	v_mul_f32_e32 v145, 0xbfb8aa3b, v57
	v_mul_f32_e32 v144, 0xbfb8aa3b, v58
	v_mul_f32_e32 v141, 0xbfb8aa3b, v59
	v_mul_f32_e32 v140, 0xbfb8aa3b, v48
	v_mul_f32_e32 v139, 0xbfb8aa3b, v49
	v_mul_f32_e32 v138, 0xbfb8aa3b, v50
	v_mul_f32_e32 v137, 0xbfb8aa3b, v51
	v_mul_f32_e32 v136, 0xbfb8aa3b, v40
	v_mul_f32_e32 v135, 0xbfb8aa3b, v41
	v_mul_f32_e32 v134, 0xbfb8aa3b, v42
	v_mul_f32_e32 v132, 0xbfb8aa3b, v43
	s_cbranch_scc1 .LBB0_124
	v_mul_f32_e32 v130, 0xbfb8aa3b, v124
	v_mul_f32_e32 v131, 0xbfb8aa3b, v125
	v_mul_f32_e32 v206, 0xbfb8aa3b, v126
	v_mul_f32_e32 v207, 0xbfb8aa3b, v127
	v_exp_f32_e32 v130, v130
	v_exp_f32_e32 v131, v131
	v_exp_f32_e32 v206, v206
	v_exp_f32_e32 v207, v207
	v_add_f32_e32 v130, 1.0, v130
	v_add_f32_e32 v131, 1.0, v131
	v_add_f32_e32 v206, 1.0, v206
	v_add_f32_e32 v207, 1.0, v207
	v_rcp_f32_e32 v130, v130
	v_rcp_f32_e32 v131, v131
	v_rcp_f32_e32 v206, v206
	v_rcp_f32_e32 v207, v207
	s_lshl_b32 s4, s50, 8
	v_cvt_pk_bf16_f32 v130, v130, v131
	s_add_i32 s4, s28, s4
	v_cvt_pk_bf16_f32 v131, v206, v207
	ds_bpermute_b32 v206, v226, v130
	ds_bpermute_b32 v207, v226, v131
	v_or_b32_e32 v180, s4, v201
	v_lshl_add_u64 v[130:131], s[40:41], 0, v[128:129]
	v_lshlrev_b64 v[208:209], 1, v[180:181]
	v_lshl_add_u64 v[130:131], v[130:131], 0, v[208:209]
	s_waitcnt lgkmcnt(0)
	global_store_dwordx2 v[130:131], v[206:207], off
	v_mul_f32_e32 v180, 0xbfb8aa3b, v116
	v_mul_f32_e32 v206, 0xbfb8aa3b, v117
	v_mul_f32_e32 v207, 0xbfb8aa3b, v118
	v_mul_f32_e32 v208, 0xbfb8aa3b, v119
	v_exp_f32_e32 v180, v180
	v_exp_f32_e32 v206, v206
	v_exp_f32_e32 v207, v207
	v_exp_f32_e32 v208, v208
	v_add_f32_e32 v180, 1.0, v180
	v_add_f32_e32 v206, 1.0, v206
	v_add_f32_e32 v207, 1.0, v207
	v_add_f32_e32 v208, 1.0, v208
	v_rcp_f32_e32 v180, v180
	v_rcp_f32_e32 v206, v206
	v_rcp_f32_e32 v207, v207
	v_rcp_f32_e32 v208, v208
	s_mov_b64 s[4:5], 0x10000
	v_cvt_pk_bf16_f32 v180, v180, v206
	ds_bpermute_b32 v206, v226, v180
	v_cvt_pk_bf16_f32 v207, v207, v208
	ds_bpermute_b32 v207, v226, v207
	v_add_f32_e32 v180, 1.0, v205
	v_add_f32_e32 v208, 1.0, v202
	v_rcp_f32_e32 v180, v180
	v_rcp_f32_e32 v208, v208
	s_waitcnt lgkmcnt(0)
	global_store_dwordx2 v[130:131], v[206:207], off offset:32
	v_add_f32_e32 v206, 1.0, v204
	v_add_f32_e32 v207, 1.0, v203
	v_rcp_f32_e32 v206, v206
	v_rcp_f32_e32 v207, v207
	v_mul_f32_e32 v227, 0xbfb8aa3b, v103
	v_exp_f32_e32 v227, v227
	v_cvt_pk_bf16_f32 v180, v180, v206
	v_cvt_pk_bf16_f32 v207, v207, v208
	ds_bpermute_b32 v206, v226, v180
	ds_bpermute_b32 v207, v226, v207
	v_add_f32_e32 v180, 1.0, v200
	v_add_f32_e32 v208, 1.0, v196
	v_rcp_f32_e32 v180, v180
	v_rcp_f32_e32 v208, v208
	s_waitcnt lgkmcnt(0)
	global_store_dwordx2 v[130:131], v[206:207], off offset:256
	v_add_f32_e32 v206, 1.0, v199
	v_add_f32_e32 v207, 1.0, v197
	v_rcp_f32_e32 v206, v206
	v_rcp_f32_e32 v207, v207
	v_add_f32_e32 v227, 1.0, v227
	v_rcp_f32_e32 v227, v227
	v_cvt_pk_bf16_f32 v180, v180, v206
	v_cvt_pk_bf16_f32 v207, v207, v208
	ds_bpermute_b32 v206, v226, v180
	ds_bpermute_b32 v207, v226, v207
	v_mul_f32_e32 v180, 0xbfb8aa3b, v108
	v_mul_f32_e32 v208, 0xbfb8aa3b, v111
	v_exp_f32_e32 v180, v180
	v_exp_f32_e32 v208, v208
	s_waitcnt lgkmcnt(0)
	global_store_dwordx2 v[130:131], v[206:207], off offset:288
	v_mul_f32_e32 v206, 0xbfb8aa3b, v109
	v_mul_f32_e32 v207, 0xbfb8aa3b, v110
	v_exp_f32_e32 v206, v206
	v_exp_f32_e32 v207, v207
	v_add_f32_e32 v180, 1.0, v180
	v_add_f32_e32 v208, 1.0, v208
	v_add_f32_e32 v206, 1.0, v206
	v_add_f32_e32 v207, 1.0, v207
	v_rcp_f32_e32 v180, v180
	v_rcp_f32_e32 v206, v206
	v_rcp_f32_e32 v207, v207
	v_rcp_f32_e32 v208, v208
	v_cvt_pk_bf16_f32 v180, v180, v206
	ds_bpermute_b32 v206, v226, v180
	v_cvt_pk_bf16_f32 v207, v207, v208
	ds_bpermute_b32 v207, v226, v207
	v_lshl_add_u64 v[208:209], v[130:131], 0, s[4:5]
	s_mov_b32 s4, 0x10000
	v_add_co_u32_e32 v228, vcc, s4, v130
	v_mul_f32_e32 v180, 0xbfb8aa3b, v100
	s_nop 0
	v_addc_co_u32_e32 v229, vcc, 0, v131, vcc
	s_waitcnt lgkmcnt(0)
	global_store_dwordx2 v[228:229], v[206:207], off
	v_mul_f32_e32 v206, 0xbfb8aa3b, v101
	v_mul_f32_e32 v207, 0xbfb8aa3b, v102
	v_exp_f32_e32 v180, v180
	v_exp_f32_e32 v206, v206
	v_exp_f32_e32 v207, v207
	s_mov_b64 s[4:5], 0x20000
	v_add_f32_e32 v180, 1.0, v180
	v_add_f32_e32 v206, 1.0, v206
	v_add_f32_e32 v207, 1.0, v207
	v_rcp_f32_e32 v180, v180
	v_rcp_f32_e32 v206, v206
	v_rcp_f32_e32 v207, v207
	v_cvt_pk_bf16_f32 v180, v180, v206
	v_cvt_pk_bf16_f32 v207, v207, v227
	ds_bpermute_b32 v206, v226, v180
	ds_bpermute_b32 v207, v226, v207
	v_add_f32_e32 v180, 1.0, v195
	v_add_f32_e32 v227, 1.0, v167
	v_rcp_f32_e32 v180, v180
	v_rcp_f32_e32 v227, v227
	s_waitcnt lgkmcnt(0)
	global_store_dwordx2 v[208:209], v[206:207], off offset:32
	v_add_f32_e32 v206, 1.0, v194
	v_add_f32_e32 v207, 1.0, v193
	v_rcp_f32_e32 v206, v206
	v_rcp_f32_e32 v207, v207
	v_cvt_pk_bf16_f32 v180, v180, v206
	v_cvt_pk_bf16_f32 v207, v207, v227
	ds_bpermute_b32 v206, v226, v180
	ds_bpermute_b32 v207, v226, v207
	v_add_f32_e32 v180, 1.0, v166
	v_add_f32_e32 v227, 1.0, v163
	v_rcp_f32_e32 v180, v180
	v_rcp_f32_e32 v227, v227
	s_waitcnt lgkmcnt(0)
	global_store_dwordx2 v[208:209], v[206:207], off offset:256
	v_add_f32_e32 v206, 1.0, v165
	v_add_f32_e32 v207, 1.0, v164
	v_rcp_f32_e32 v206, v206
	v_rcp_f32_e32 v207, v207
	v_cvt_pk_bf16_f32 v180, v180, v206
	v_cvt_pk_bf16_f32 v207, v207, v227
	ds_bpermute_b32 v206, v226, v180
	ds_bpermute_b32 v207, v226, v207
	v_mul_f32_e32 v180, 0xbfb8aa3b, v92
	v_exp_f32_e32 v180, v180
	v_mul_f32_e32 v227, 0xbfb8aa3b, v87
	v_exp_f32_e32 v227, v227
	s_waitcnt lgkmcnt(0)
	global_store_dwordx2 v[208:209], v[206:207], off offset:288
	v_mul_f32_e32 v206, 0xbfb8aa3b, v93
	v_mul_f32_e32 v207, 0xbfb8aa3b, v94
	v_mul_f32_e32 v208, 0xbfb8aa3b, v95
	v_exp_f32_e32 v206, v206
	v_exp_f32_e32 v207, v207
	v_exp_f32_e32 v208, v208
	v_add_f32_e32 v180, 1.0, v180
	v_add_f32_e32 v206, 1.0, v206
	v_add_f32_e32 v207, 1.0, v207
	v_add_f32_e32 v208, 1.0, v208
	v_rcp_f32_e32 v180, v180
	v_rcp_f32_e32 v206, v206
	v_rcp_f32_e32 v207, v207
	v_rcp_f32_e32 v208, v208
	v_add_f32_e32 v227, 1.0, v227
	v_cvt_pk_bf16_f32 v180, v180, v206
	ds_bpermute_b32 v206, v226, v180
	v_cvt_pk_bf16_f32 v207, v207, v208
	ds_bpermute_b32 v207, v226, v207
	v_lshl_add_u64 v[208:209], v[130:131], 0, s[4:5]
	s_mov_b32 s4, 0x20000
	v_add_co_u32_e32 v228, vcc, s4, v130
	v_mul_f32_e32 v180, 0xbfb8aa3b, v84
	s_nop 0
	v_addc_co_u32_e32 v229, vcc, 0, v131, vcc
	s_waitcnt lgkmcnt(0)
	global_store_dwordx2 v[228:229], v[206:207], off
	v_mul_f32_e32 v206, 0xbfb8aa3b, v85
	v_mul_f32_e32 v207, 0xbfb8aa3b, v86
	v_exp_f32_e32 v180, v180
	v_exp_f32_e32 v206, v206
	v_exp_f32_e32 v207, v207
	v_rcp_f32_e32 v227, v227
	v_add_f32_e32 v180, 1.0, v180
	v_add_f32_e32 v206, 1.0, v206
	v_add_f32_e32 v207, 1.0, v207
	v_rcp_f32_e32 v180, v180
	v_rcp_f32_e32 v206, v206
	v_rcp_f32_e32 v207, v207
	s_mov_b64 s[4:5], 0x30000
	v_cvt_pk_bf16_f32 v180, v180, v206
	v_cvt_pk_bf16_f32 v207, v207, v227
	ds_bpermute_b32 v206, v226, v180
	ds_bpermute_b32 v207, v226, v207
	v_add_f32_e32 v180, 1.0, v162
	v_add_f32_e32 v227, 1.0, v159
	v_rcp_f32_e32 v180, v180
	v_rcp_f32_e32 v227, v227
	s_waitcnt lgkmcnt(0)
	global_store_dwordx2 v[208:209], v[206:207], off offset:32
	v_add_f32_e32 v206, 1.0, v161
	v_add_f32_e32 v207, 1.0, v160
	v_rcp_f32_e32 v206, v206
	v_rcp_f32_e32 v207, v207
	v_cvt_pk_bf16_f32 v180, v180, v206
	v_cvt_pk_bf16_f32 v207, v207, v227
	ds_bpermute_b32 v206, v226, v180
	ds_bpermute_b32 v207, v226, v207
	v_add_f32_e32 v180, 1.0, v158
	v_add_f32_e32 v227, 1.0, v155
	v_rcp_f32_e32 v180, v180
	v_rcp_f32_e32 v227, v227
	s_waitcnt lgkmcnt(0)
	global_store_dwordx2 v[208:209], v[206:207], off offset:256
	v_add_f32_e32 v206, 1.0, v157
	v_add_f32_e32 v207, 1.0, v156
	v_rcp_f32_e32 v206, v206
	v_rcp_f32_e32 v207, v207
	v_cvt_pk_bf16_f32 v180, v180, v206
	v_cvt_pk_bf16_f32 v207, v207, v227
	ds_bpermute_b32 v206, v226, v180
	ds_bpermute_b32 v207, v226, v207
	v_mul_f32_e32 v180, 0xbfb8aa3b, v76
	v_exp_f32_e32 v180, v180
	v_mul_f32_e32 v227, 0xbfb8aa3b, v71
	v_exp_f32_e32 v227, v227
	s_waitcnt lgkmcnt(0)
	global_store_dwordx2 v[208:209], v[206:207], off offset:288
	v_mul_f32_e32 v206, 0xbfb8aa3b, v77
	v_mul_f32_e32 v207, 0xbfb8aa3b, v78
	v_mul_f32_e32 v208, 0xbfb8aa3b, v79
	v_exp_f32_e32 v206, v206
	v_exp_f32_e32 v207, v207
	v_exp_f32_e32 v208, v208
	v_add_f32_e32 v180, 1.0, v180
	v_add_f32_e32 v206, 1.0, v206
	v_add_f32_e32 v207, 1.0, v207
	v_add_f32_e32 v208, 1.0, v208
	v_rcp_f32_e32 v180, v180
	v_rcp_f32_e32 v206, v206
	v_rcp_f32_e32 v207, v207
	v_rcp_f32_e32 v208, v208
	v_add_f32_e32 v227, 1.0, v227
	v_cvt_pk_bf16_f32 v180, v180, v206
	ds_bpermute_b32 v206, v226, v180
	v_cvt_pk_bf16_f32 v207, v207, v208
	ds_bpermute_b32 v207, v226, v207
	v_lshl_add_u64 v[208:209], v[130:131], 0, s[4:5]
	s_mov_b32 s4, 0x30000
	v_add_co_u32_e32 v228, vcc, s4, v130
	v_mul_f32_e32 v180, 0xbfb8aa3b, v68
	s_nop 0
	v_addc_co_u32_e32 v229, vcc, 0, v131, vcc
	s_waitcnt lgkmcnt(0)
	global_store_dwordx2 v[228:229], v[206:207], off
	v_mul_f32_e32 v206, 0xbfb8aa3b, v69
	v_mul_f32_e32 v207, 0xbfb8aa3b, v70
	v_exp_f32_e32 v180, v180
	v_exp_f32_e32 v206, v206
	v_exp_f32_e32 v207, v207
	v_rcp_f32_e32 v227, v227
	v_add_f32_e32 v180, 1.0, v180
	v_add_f32_e32 v206, 1.0, v206
	v_add_f32_e32 v207, 1.0, v207
	v_rcp_f32_e32 v180, v180
	v_rcp_f32_e32 v206, v206
	v_rcp_f32_e32 v207, v207
	s_mov_b64 s[4:5], 0x80000
	v_cvt_pk_bf16_f32 v180, v180, v206
	v_cvt_pk_bf16_f32 v207, v207, v227
	ds_bpermute_b32 v206, v226, v180
	ds_bpermute_b32 v207, v226, v207
	v_add_f32_e32 v180, 1.0, v154
	v_add_f32_e32 v227, 1.0, v151
	v_rcp_f32_e32 v180, v180
	v_rcp_f32_e32 v227, v227
	s_waitcnt lgkmcnt(0)
	global_store_dwordx2 v[208:209], v[206:207], off offset:32
	v_add_f32_e32 v206, 1.0, v153
	v_add_f32_e32 v207, 1.0, v152
	v_rcp_f32_e32 v206, v206
	v_rcp_f32_e32 v207, v207
	v_cvt_pk_bf16_f32 v180, v180, v206
	v_cvt_pk_bf16_f32 v207, v207, v227
	ds_bpermute_b32 v206, v226, v180
	ds_bpermute_b32 v207, v226, v207
	v_add_f32_e32 v180, 1.0, v150
	v_add_f32_e32 v227, 1.0, v147
	v_rcp_f32_e32 v180, v180
	v_rcp_f32_e32 v227, v227
	s_waitcnt lgkmcnt(0)
	global_store_dwordx2 v[208:209], v[206:207], off offset:256
	v_add_f32_e32 v206, 1.0, v149
	v_add_f32_e32 v207, 1.0, v148
	v_rcp_f32_e32 v206, v206
	v_rcp_f32_e32 v207, v207
	v_cvt_pk_bf16_f32 v180, v180, v206
	v_cvt_pk_bf16_f32 v207, v207, v227
	ds_bpermute_b32 v206, v226, v180
	ds_bpermute_b32 v207, v226, v207
	v_mul_f32_e32 v180, 0xbfb8aa3b, v60
	v_exp_f32_e32 v180, v180
	v_mul_f32_e32 v227, 0xbfb8aa3b, v55
	v_exp_f32_e32 v227, v227
	s_waitcnt lgkmcnt(0)
	global_store_dwordx2 v[208:209], v[206:207], off offset:288
	v_mul_f32_e32 v206, 0xbfb8aa3b, v61
	v_mul_f32_e32 v207, 0xbfb8aa3b, v62
	v_mul_f32_e32 v208, 0xbfb8aa3b, v63
	v_exp_f32_e32 v206, v206
	v_exp_f32_e32 v207, v207
	v_exp_f32_e32 v208, v208
	v_add_f32_e32 v180, 1.0, v180
	v_add_f32_e32 v206, 1.0, v206
	v_add_f32_e32 v207, 1.0, v207
	v_add_f32_e32 v208, 1.0, v208
	v_rcp_f32_e32 v180, v180
	v_rcp_f32_e32 v206, v206
	v_rcp_f32_e32 v207, v207
	v_rcp_f32_e32 v208, v208
	v_add_f32_e32 v227, 1.0, v227
	v_cvt_pk_bf16_f32 v180, v180, v206
	ds_bpermute_b32 v206, v226, v180
	v_cvt_pk_bf16_f32 v207, v207, v208
	ds_bpermute_b32 v207, v226, v207
	v_lshl_add_u64 v[208:209], v[130:131], 0, s[4:5]
	s_mov_b32 s4, 0x80000
	v_add_co_u32_e32 v228, vcc, s4, v130
	v_mul_f32_e32 v180, 0xbfb8aa3b, v52
	s_nop 0
	v_addc_co_u32_e32 v229, vcc, 0, v131, vcc
	s_waitcnt lgkmcnt(0)
	global_store_dwordx2 v[228:229], v[206:207], off
	v_mul_f32_e32 v206, 0xbfb8aa3b, v53
	v_mul_f32_e32 v207, 0xbfb8aa3b, v54
	v_exp_f32_e32 v180, v180
	v_exp_f32_e32 v206, v206
	v_exp_f32_e32 v207, v207
	v_rcp_f32_e32 v227, v227
	v_add_f32_e32 v180, 1.0, v180
	v_add_f32_e32 v206, 1.0, v206
	v_add_f32_e32 v207, 1.0, v207
	v_rcp_f32_e32 v180, v180
	v_rcp_f32_e32 v206, v206
	v_rcp_f32_e32 v207, v207
	s_mov_b64 s[4:5], 0x90000
	v_cvt_pk_bf16_f32 v180, v180, v206
	v_cvt_pk_bf16_f32 v207, v207, v227
	ds_bpermute_b32 v206, v226, v180
	ds_bpermute_b32 v207, v226, v207
	v_exp_f32_e32 v180, v146
	v_exp_f32_e32 v227, v141
	s_waitcnt lgkmcnt(0)
	global_store_dwordx2 v[208:209], v[206:207], off offset:32
	v_exp_f32_e32 v206, v145
	v_exp_f32_e32 v207, v144
	v_add_f32_e32 v180, 1.0, v180
	v_add_f32_e32 v227, 1.0, v227
	v_add_f32_e32 v206, 1.0, v206
	v_add_f32_e32 v207, 1.0, v207
	v_rcp_f32_e32 v180, v180
	v_rcp_f32_e32 v206, v206
	v_rcp_f32_e32 v207, v207
	v_rcp_f32_e32 v227, v227
	v_cvt_pk_bf16_f32 v180, v180, v206
	ds_bpermute_b32 v206, v226, v180
	v_cvt_pk_bf16_f32 v207, v207, v227
	ds_bpermute_b32 v207, v226, v207
	v_exp_f32_e32 v180, v140
	v_exp_f32_e32 v227, v137
	s_waitcnt lgkmcnt(0)
	global_store_dwordx2 v[208:209], v[206:207], off offset:256
	v_exp_f32_e32 v206, v139
	v_exp_f32_e32 v207, v138
	v_add_f32_e32 v180, 1.0, v180
	v_add_f32_e32 v227, 1.0, v227
	v_add_f32_e32 v206, 1.0, v206
	v_add_f32_e32 v207, 1.0, v207
	v_rcp_f32_e32 v180, v180
	v_rcp_f32_e32 v206, v206
	v_rcp_f32_e32 v207, v207
	v_rcp_f32_e32 v227, v227
	v_cvt_pk_bf16_f32 v180, v180, v206
	ds_bpermute_b32 v206, v226, v180
	v_cvt_pk_bf16_f32 v207, v207, v227
	ds_bpermute_b32 v207, v226, v207
	v_mul_f32_e32 v180, 0xbfb8aa3b, v44
	v_exp_f32_e32 v180, v180
	v_mul_f32_e32 v227, 0xbfb8aa3b, v39
	v_exp_f32_e32 v227, v227
	s_waitcnt lgkmcnt(0)
	global_store_dwordx2 v[208:209], v[206:207], off offset:288
	v_mul_f32_e32 v206, 0xbfb8aa3b, v45
	v_mul_f32_e32 v207, 0xbfb8aa3b, v46
	v_mul_f32_e32 v208, 0xbfb8aa3b, v47
	v_exp_f32_e32 v206, v206
	v_exp_f32_e32 v207, v207
	v_exp_f32_e32 v208, v208
	v_add_f32_e32 v180, 1.0, v180
	v_add_f32_e32 v206, 1.0, v206
	v_add_f32_e32 v207, 1.0, v207
	v_add_f32_e32 v208, 1.0, v208
	v_rcp_f32_e32 v180, v180
	v_rcp_f32_e32 v206, v206
	v_rcp_f32_e32 v207, v207
	v_rcp_f32_e32 v208, v208
	v_add_f32_e32 v227, 1.0, v227
	v_cvt_pk_bf16_f32 v180, v180, v206
	ds_bpermute_b32 v206, v226, v180
	v_cvt_pk_bf16_f32 v207, v207, v208
	ds_bpermute_b32 v207, v226, v207
	v_lshl_add_u64 v[208:209], v[130:131], 0, s[4:5]
	s_mov_b32 s4, 0x90000
	v_add_co_u32_e32 v228, vcc, s4, v130
	v_mul_f32_e32 v180, 0xbfb8aa3b, v36
	s_nop 0
	v_addc_co_u32_e32 v229, vcc, 0, v131, vcc
	s_waitcnt lgkmcnt(0)
	global_store_dwordx2 v[228:229], v[206:207], off
	v_mul_f32_e32 v206, 0xbfb8aa3b, v37
	v_mul_f32_e32 v207, 0xbfb8aa3b, v38
	v_exp_f32_e32 v180, v180
	v_exp_f32_e32 v206, v206
	v_exp_f32_e32 v207, v207
	v_rcp_f32_e32 v227, v227
	v_add_f32_e32 v180, 1.0, v180
	v_add_f32_e32 v206, 1.0, v206
	v_add_f32_e32 v207, 1.0, v207
	v_rcp_f32_e32 v180, v180
	v_rcp_f32_e32 v206, v206
	v_rcp_f32_e32 v207, v207
	s_mov_b64 s[4:5], 0xa0000
	v_cvt_pk_bf16_f32 v180, v180, v206
	v_cvt_pk_bf16_f32 v207, v207, v227
	ds_bpermute_b32 v206, v226, v180
	ds_bpermute_b32 v207, v226, v207
	v_exp_f32_e32 v180, v136
	v_exp_f32_e32 v227, v132
	s_waitcnt lgkmcnt(0)
	global_store_dwordx2 v[208:209], v[206:207], off offset:32
	v_exp_f32_e32 v206, v135
	v_exp_f32_e32 v207, v134
	v_add_f32_e32 v180, 1.0, v180
	v_add_f32_e32 v227, 1.0, v227
	v_add_f32_e32 v206, 1.0, v206
	v_add_f32_e32 v207, 1.0, v207
	v_rcp_f32_e32 v180, v180
	v_rcp_f32_e32 v206, v206
	v_rcp_f32_e32 v207, v207
	v_rcp_f32_e32 v227, v227
	v_cvt_pk_bf16_f32 v180, v180, v206
	ds_bpermute_b32 v206, v226, v180
	v_cvt_pk_bf16_f32 v207, v207, v227
	ds_bpermute_b32 v207, v226, v207
	v_mul_f32_e32 v180, 0xbfb8aa3b, v32
	v_mul_f32_e32 v227, 0xbfb8aa3b, v35
	v_exp_f32_e32 v180, v180
	v_exp_f32_e32 v227, v227
	s_waitcnt lgkmcnt(0)
	global_store_dwordx2 v[208:209], v[206:207], off offset:256
	v_mul_f32_e32 v206, 0xbfb8aa3b, v33
	v_mul_f32_e32 v207, 0xbfb8aa3b, v34
	v_exp_f32_e32 v206, v206
	v_exp_f32_e32 v207, v207
	v_add_f32_e32 v180, 1.0, v180
	v_add_f32_e32 v227, 1.0, v227
	v_add_f32_e32 v206, 1.0, v206
	v_add_f32_e32 v207, 1.0, v207
	v_rcp_f32_e32 v180, v180
	v_rcp_f32_e32 v206, v206
	v_rcp_f32_e32 v207, v207
	v_rcp_f32_e32 v227, v227
	v_cvt_pk_bf16_f32 v180, v180, v206
	ds_bpermute_b32 v206, v226, v180
	v_cvt_pk_bf16_f32 v207, v207, v227
	ds_bpermute_b32 v207, v226, v207
	v_mul_f32_e32 v180, 0xbfb8aa3b, v28
	v_exp_f32_e32 v180, v180
	v_mul_f32_e32 v227, 0xbfb8aa3b, v23
	v_exp_f32_e32 v227, v227
	s_waitcnt lgkmcnt(0)
	global_store_dwordx2 v[208:209], v[206:207], off offset:288
	v_mul_f32_e32 v206, 0xbfb8aa3b, v29
	v_mul_f32_e32 v207, 0xbfb8aa3b, v30
	v_mul_f32_e32 v208, 0xbfb8aa3b, v31
	v_exp_f32_e32 v206, v206
	v_exp_f32_e32 v207, v207
	v_exp_f32_e32 v208, v208
	v_add_f32_e32 v180, 1.0, v180
	v_add_f32_e32 v206, 1.0, v206
	v_add_f32_e32 v207, 1.0, v207
	v_add_f32_e32 v208, 1.0, v208
	v_rcp_f32_e32 v180, v180
	v_rcp_f32_e32 v206, v206
	v_rcp_f32_e32 v207, v207
	v_rcp_f32_e32 v208, v208
	v_add_f32_e32 v227, 1.0, v227
	v_cvt_pk_bf16_f32 v180, v180, v206
	ds_bpermute_b32 v206, v226, v180
	v_cvt_pk_bf16_f32 v207, v207, v208
	ds_bpermute_b32 v207, v226, v207
	v_lshl_add_u64 v[208:209], v[130:131], 0, s[4:5]
	s_mov_b32 s4, 0xa0000
	v_add_co_u32_e32 v228, vcc, s4, v130
	v_mul_f32_e32 v180, 0xbfb8aa3b, v20
	s_nop 0
	v_addc_co_u32_e32 v229, vcc, 0, v131, vcc
	s_waitcnt lgkmcnt(0)
	global_store_dwordx2 v[228:229], v[206:207], off
	v_mul_f32_e32 v206, 0xbfb8aa3b, v21
	v_mul_f32_e32 v207, 0xbfb8aa3b, v22
	v_exp_f32_e32 v180, v180
	v_exp_f32_e32 v206, v206
	v_exp_f32_e32 v207, v207
	v_rcp_f32_e32 v227, v227
	v_add_f32_e32 v180, 1.0, v180
	v_add_f32_e32 v206, 1.0, v206
	v_add_f32_e32 v207, 1.0, v207
	v_rcp_f32_e32 v180, v180
	v_rcp_f32_e32 v206, v206
	v_rcp_f32_e32 v207, v207
	s_mov_b64 s[4:5], 0xb0000
	v_cvt_pk_bf16_f32 v180, v180, v206
	v_cvt_pk_bf16_f32 v207, v207, v227
	ds_bpermute_b32 v206, v226, v180
	ds_bpermute_b32 v207, v226, v207
	v_mul_f32_e32 v180, 0xbfb8aa3b, v24
	v_mul_f32_e32 v227, 0xbfb8aa3b, v27
	v_exp_f32_e32 v180, v180
	v_exp_f32_e32 v227, v227
	s_waitcnt lgkmcnt(0)
	global_store_dwordx2 v[208:209], v[206:207], off offset:32
	v_mul_f32_e32 v206, 0xbfb8aa3b, v25
	v_mul_f32_e32 v207, 0xbfb8aa3b, v26
	v_exp_f32_e32 v206, v206
	v_exp_f32_e32 v207, v207
	v_add_f32_e32 v180, 1.0, v180
	v_add_f32_e32 v227, 1.0, v227
	v_add_f32_e32 v206, 1.0, v206
	v_add_f32_e32 v207, 1.0, v207
	v_rcp_f32_e32 v180, v180
	v_rcp_f32_e32 v206, v206
	v_rcp_f32_e32 v207, v207
	v_rcp_f32_e32 v227, v227
	v_cvt_pk_bf16_f32 v180, v180, v206
	ds_bpermute_b32 v206, v226, v180
	v_cvt_pk_bf16_f32 v207, v207, v227
	ds_bpermute_b32 v207, v226, v207
	v_mul_f32_e32 v180, 0xbfb8aa3b, v16
	v_mul_f32_e32 v227, 0xbfb8aa3b, v19
	v_exp_f32_e32 v180, v180
	v_exp_f32_e32 v227, v227
	s_waitcnt lgkmcnt(0)
	global_store_dwordx2 v[208:209], v[206:207], off offset:256
	v_mul_f32_e32 v206, 0xbfb8aa3b, v17
	v_mul_f32_e32 v207, 0xbfb8aa3b, v18
	v_exp_f32_e32 v206, v206
	v_exp_f32_e32 v207, v207
	v_add_f32_e32 v180, 1.0, v180
	v_add_f32_e32 v227, 1.0, v227
	v_add_f32_e32 v206, 1.0, v206
	v_add_f32_e32 v207, 1.0, v207
	v_rcp_f32_e32 v180, v180
	v_rcp_f32_e32 v206, v206
	v_rcp_f32_e32 v207, v207
	v_rcp_f32_e32 v227, v227
	v_cvt_pk_bf16_f32 v180, v180, v206
	ds_bpermute_b32 v206, v226, v180
	v_cvt_pk_bf16_f32 v207, v207, v227
	ds_bpermute_b32 v207, v226, v207
	v_mul_f32_e32 v180, 0xbfb8aa3b, v12
	v_exp_f32_e32 v180, v180
	s_waitcnt lgkmcnt(0)
	global_store_dwordx2 v[208:209], v[206:207], off offset:288
	v_mul_f32_e32 v206, 0xbfb8aa3b, v13
	v_mul_f32_e32 v207, 0xbfb8aa3b, v14
	v_mul_f32_e32 v208, 0xbfb8aa3b, v15
	v_exp_f32_e32 v206, v206
	v_exp_f32_e32 v207, v207
	v_exp_f32_e32 v208, v208
	v_add_f32_e32 v180, 1.0, v180
	v_add_f32_e32 v206, 1.0, v206
	v_add_f32_e32 v207, 1.0, v207
	v_add_f32_e32 v208, 1.0, v208
	v_rcp_f32_e32 v180, v180
	v_rcp_f32_e32 v206, v206
	v_rcp_f32_e32 v207, v207
	v_rcp_f32_e32 v208, v208
	v_cvt_pk_bf16_f32 v180, v180, v206
	ds_bpermute_b32 v206, v226, v180
	v_cvt_pk_bf16_f32 v207, v207, v208
	ds_bpermute_b32 v207, v226, v207
	v_lshl_add_u64 v[208:209], v[130:131], 0, s[4:5]
	s_mov_b32 s4, 0xb0000
	v_add_co_u32_e32 v130, vcc, s4, v130
	v_mul_f32_e32 v180, 0xbfb8aa3b, v6
	s_nop 0
	v_addc_co_u32_e32 v131, vcc, 0, v131, vcc
	s_waitcnt lgkmcnt(0)
	global_store_dwordx2 v[130:131], v[206:207], off
	v_mul_f32_e32 v130, 0xbfb8aa3b, v4
	v_mul_f32_e32 v131, 0xbfb8aa3b, v5
	v_mul_f32_e32 v206, 0xbfb8aa3b, v7
	v_exp_f32_e32 v130, v130
	v_exp_f32_e32 v131, v131
	v_exp_f32_e32 v180, v180
	v_exp_f32_e32 v206, v206
	v_add_f32_e32 v130, 1.0, v130
	v_add_f32_e32 v131, 1.0, v131
	v_add_f32_e32 v180, 1.0, v180
	v_add_f32_e32 v206, 1.0, v206
	v_rcp_f32_e32 v130, v130
	v_rcp_f32_e32 v131, v131
	v_rcp_f32_e32 v180, v180
	v_rcp_f32_e32 v206, v206
	s_mov_b64 s[4:5], 0
	v_cvt_pk_bf16_f32 v130, v130, v131
	ds_bpermute_b32 v130, v226, v130
	v_cvt_pk_bf16_f32 v131, v180, v206
	ds_bpermute_b32 v131, v226, v131
	v_mul_f32_e32 v180, 0xbfb8aa3b, v10
	v_mul_f32_e32 v206, 0xbfb8aa3b, v11
	v_exp_f32_e32 v180, v180
	v_exp_f32_e32 v206, v206
	s_waitcnt lgkmcnt(0)
	global_store_dwordx2 v[208:209], v[130:131], off offset:32
	v_mul_f32_e32 v130, 0xbfb8aa3b, v8
	v_mul_f32_e32 v131, 0xbfb8aa3b, v9
	v_exp_f32_e32 v130, v130
	v_exp_f32_e32 v131, v131
	v_add_f32_e32 v180, 1.0, v180
	v_add_f32_e32 v206, 1.0, v206
	v_add_f32_e32 v130, 1.0, v130
	v_add_f32_e32 v131, 1.0, v131
	v_rcp_f32_e32 v130, v130
	v_rcp_f32_e32 v131, v131
	v_rcp_f32_e32 v180, v180
	v_rcp_f32_e32 v206, v206
	v_cvt_pk_bf16_f32 v130, v130, v131
	ds_bpermute_b32 v130, v226, v130
	v_cvt_pk_bf16_f32 v131, v180, v206
	ds_bpermute_b32 v131, v226, v131
	v_mul_f32_e32 v180, 0xbfb8aa3b, v2
	v_mul_f32_e32 v206, 0xbfb8aa3b, v3
	v_exp_f32_e32 v180, v180
	v_exp_f32_e32 v206, v206
	s_waitcnt lgkmcnt(0)
	global_store_dwordx2 v[208:209], v[130:131], off offset:256
	v_mul_f32_e32 v130, 0xbfb8aa3b, v0
	v_mul_f32_e32 v131, 0xbfb8aa3b, v1
	v_exp_f32_e32 v130, v130
	v_exp_f32_e32 v131, v131
	v_add_f32_e32 v180, 1.0, v180
	v_add_f32_e32 v206, 1.0, v206
	v_add_f32_e32 v130, 1.0, v130
	v_add_f32_e32 v131, 1.0, v131
	v_rcp_f32_e32 v130, v130
	v_rcp_f32_e32 v131, v131
	v_rcp_f32_e32 v180, v180
	v_rcp_f32_e32 v206, v206
	v_cvt_pk_bf16_f32 v130, v130, v131
	ds_bpermute_b32 v130, v226, v130
	v_cvt_pk_bf16_f32 v131, v180, v206
	ds_bpermute_b32 v131, v226, v131
	s_waitcnt lgkmcnt(0)
	global_store_dwordx2 v[208:209], v[130:131], off offset:288

.LBB0_1167:
	ds_read_b128 v[148:151], v143
	ds_read_b128 v[152:155], v143 offset:1024
	ds_read_b128 v[156:159], v143 offset:2048
	ds_read_b128 v[160:163], v143 offset:3072


	s_add_i32 m0, s21, 0xc000
	ds_read_b128 v[164:167], v145
	ds_read_b128 v[176:179], v145 offset:1024
	ds_read_b128 v[180:183], v145 offset:2048
	ds_read_b128 v[184:187], v145 offset:3072
	ds_read_b128 v[188:191], v145 offset:4096
	ds_read_b128 v[192:195], v145 offset:5120
	ds_read_b128 v[196:199], v145 offset:6144
	ds_read_b128 v[200:203], v145 offset:7168
	global_load_lds_dwordx4 v128, s[22:23]
	s_add_i32 m0, s21, 0xe000
	s_nop 0

	global_load_lds_dwordx4 v130, s[22:23]
	s_add_u32 s24, s22, 0xfff80080
	s_addc_u32 s25, s23, -1
	s_cmp_eq_u32 s53, 28
	s_cselect_b32 s27, s15, s25
	s_cselect_b32 s26, s49, s24
	s_cselect_b32 s25, s13, s52
	s_cselect_b32 s24, s50, s51
	s_waitcnt lgkmcnt(8)
	s_barrier
	s_waitcnt lgkmcnt(0)


	v_mfma_f32_16x16x32_bf16 v[124:127], v[148:151], v[164:167], v[124:127]
	v_mfma_f32_16x16x32_bf16 v[120:123], v[156:159], v[164:167], v[120:123]
	v_mfma_f32_16x16x32_bf16 v[116:119], v[148:151], v[180:183], v[116:119]
	v_mfma_f32_16x16x32_bf16 v[104:107], v[156:159], v[180:183], v[104:107]
	v_mfma_f32_16x16x32_bf16 v[96:99], v[148:151], v[188:191], v[96:99]
	v_mfma_f32_16x16x32_bf16 v[88:91], v[156:159], v[188:191], v[88:91]
	v_mfma_f32_16x16x32_bf16 v[80:83], v[148:151], v[196:199], v[80:83]
	v_mfma_f32_16x16x32_bf16 v[72:75], v[156:159], v[196:199], v[72:75]
	v_mfma_f32_16x16x32_bf16 v[124:127], v[152:155], v[176:179], v[124:127]
	v_mfma_f32_16x16x32_bf16 v[120:123], v[160:163], v[176:179], v[120:123]
	v_mfma_f32_16x16x32_bf16 v[116:119], v[152:155], v[184:187], v[116:119]
	v_mfma_f32_16x16x32_bf16 v[104:107], v[160:163], v[184:187], v[104:107]
	v_mfma_f32_16x16x32_bf16 v[96:99], v[152:155], v[192:195], v[96:99]
	v_mfma_f32_16x16x32_bf16 v[88:91], v[160:163], v[192:195], v[88:91]
	v_mfma_f32_16x16x32_bf16 v[80:83], v[152:155], v[200:203], v[80:83]
	v_mfma_f32_16x16x32_bf16 v[72:75], v[160:163], v[200:203], v[72:75]

	s_barrier
	s_add_i32 s54, s45, s31
	s_add_u32 s66, s24, s10
	s_addc_u32 s67, s25, s11
	s_mov_b32 m0, s54
	ds_read_b128 v[204:207], v147
	ds_read_b128 v[218:221], v147 offset:1024
	ds_read_b128 v[222:225], v147 offset:2048
	ds_read_b128 v[226:229], v147 offset:3072
	global_load_lds_dwordx4 v172, s[24:25]
	s_add_i32 m0, s54, 0x2000
	s_nop 0

	global_load_lds_dwordx4 v174, s[24:25]
	s_barrier
	s_waitcnt lgkmcnt(0)


	v_mfma_f32_16x16x32_bf16 v[112:115], v[204:207], v[164:167], v[112:115]
	v_mfma_f32_16x16x32_bf16 v[108:111], v[222:225], v[164:167], v[108:111]
	v_mfma_f32_16x16x32_bf16 v[100:103], v[204:207], v[180:183], v[100:103]
	v_mfma_f32_16x16x32_bf16 v[92:95], v[222:225], v[180:183], v[92:95]
	v_mfma_f32_16x16x32_bf16 v[84:87], v[204:207], v[188:191], v[84:87]
	v_mfma_f32_16x16x32_bf16 v[76:79], v[222:225], v[188:191], v[76:79]
	v_mfma_f32_16x16x32_bf16 v[68:71], v[204:207], v[196:199], v[68:71]
	v_mfma_f32_16x16x32_bf16 v[64:67], v[222:225], v[196:199], v[64:67]
	v_mfma_f32_16x16x32_bf16 v[112:115], v[218:221], v[176:179], v[112:115]
	v_mfma_f32_16x16x32_bf16 v[108:111], v[226:229], v[176:179], v[108:111]
	v_mfma_f32_16x16x32_bf16 v[100:103], v[218:221], v[184:187], v[100:103]
	v_mfma_f32_16x16x32_bf16 v[92:95], v[226:229], v[184:187], v[92:95]
	v_mfma_f32_16x16x32_bf16 v[84:87], v[218:221], v[192:195], v[84:87]
	v_mfma_f32_16x16x32_bf16 v[76:79], v[226:229], v[192:195], v[76:79]
	v_mfma_f32_16x16x32_bf16 v[68:71], v[218:221], v[200:203], v[68:71]
	v_mfma_f32_16x16x32_bf16 v[64:67], v[226:229], v[200:203], v[64:67]

	s_mov_b32 m0, s21
	s_add_u32 s68, s26, s10
	s_addc_u32 s69, s27, s11
	s_barrier
	ds_read_b128 v[164:167], v145 offset:16384
	ds_read_b128 v[176:179], v145 offset:17408
	ds_read_b128 v[180:183], v145 offset:18432
	ds_read_b128 v[184:187], v145 offset:19456
	ds_read_b128 v[188:191], v145 offset:20480
	ds_read_b128 v[192:195], v145 offset:21504
	ds_read_b128 v[196:199], v145 offset:22528
	ds_read_b128 v[200:203], v145 offset:23552
	global_load_lds_dwordx4 v172, s[26:27]
	s_mov_b32 m0, s35
	s_nop 0

	global_load_lds_dwordx4 v174, s[26:27]
	s_barrier
	s_waitcnt lgkmcnt(0)


	v_mfma_f32_16x16x32_bf16 v[60:63], v[148:151], v[164:167], v[60:63]
	v_mfma_f32_16x16x32_bf16 v[56:59], v[156:159], v[164:167], v[56:59]
	v_mfma_f32_16x16x32_bf16 v[48:51], v[148:151], v[180:183], v[48:51]
	v_mfma_f32_16x16x32_bf16 v[40:43], v[156:159], v[180:183], v[40:43]
	v_mfma_f32_16x16x32_bf16 v[32:35], v[148:151], v[188:191], v[32:35]
	v_mfma_f32_16x16x32_bf16 v[24:27], v[156:159], v[188:191], v[24:27]
	v_mfma_f32_16x16x32_bf16 v[16:19], v[148:151], v[196:199], v[16:19]
	v_mfma_f32_16x16x32_bf16 v[8:11], v[156:159], v[196:199], v[8:11]
	v_mfma_f32_16x16x32_bf16 v[60:63], v[152:155], v[176:179], v[60:63]
	v_mfma_f32_16x16x32_bf16 v[56:59], v[160:163], v[176:179], v[56:59]
	v_mfma_f32_16x16x32_bf16 v[48:51], v[152:155], v[184:187], v[48:51]
	v_mfma_f32_16x16x32_bf16 v[40:43], v[160:163], v[184:187], v[40:43]
	v_mfma_f32_16x16x32_bf16 v[32:35], v[152:155], v[192:195], v[32:35]
	v_mfma_f32_16x16x32_bf16 v[24:27], v[160:163], v[192:195], v[24:27]
	v_mfma_f32_16x16x32_bf16 v[16:19], v[152:155], v[200:203], v[16:19]
	v_mfma_f32_16x16x32_bf16 v[8:11], v[160:163], v[200:203], v[8:11]

	s_barrier
	s_add_u32 s54, s24, 0x80000
	s_addc_u32 s55, s25, 0
	s_add_i32 s56, s46, s31
	s_mov_b32 m0, s56
	s_nop 0

	global_load_lds_dwordx4 v172, s[54:55]
	s_add_i32 m0, s56, 0x2000
	s_nop 0

	global_load_lds_dwordx4 v174, s[54:55]
	s_waitcnt vmcnt(6)
	s_barrier

	v_mfma_f32_16x16x32_bf16 v[52:55], v[204:207], v[164:167], v[52:55]
	v_mfma_f32_16x16x32_bf16 v[44:47], v[222:225], v[164:167], v[44:47]
	v_mfma_f32_16x16x32_bf16 v[36:39], v[204:207], v[180:183], v[36:39]
	v_mfma_f32_16x16x32_bf16 v[28:31], v[222:225], v[180:183], v[28:31]
	v_mfma_f32_16x16x32_bf16 v[20:23], v[204:207], v[188:191], v[20:23]
	v_mfma_f32_16x16x32_bf16 v[12:15], v[222:225], v[188:191], v[12:15]
	v_mfma_f32_16x16x32_bf16 v[4:7], v[204:207], v[196:199], v[4:7]
	v_mfma_f32_16x16x32_bf16 v[0:3], v[222:225], v[196:199], v[0:3]
	v_mfma_f32_16x16x32_bf16 v[52:55], v[218:221], v[176:179], v[52:55]
	v_mfma_f32_16x16x32_bf16 v[44:47], v[226:229], v[176:179], v[44:47]
	v_mfma_f32_16x16x32_bf16 v[36:39], v[218:221], v[184:187], v[36:39]
	v_mfma_f32_16x16x32_bf16 v[28:31], v[226:229], v[184:187], v[28:31]
	v_mfma_f32_16x16x32_bf16 v[20:23], v[218:221], v[192:195], v[20:23]
	v_mfma_f32_16x16x32_bf16 v[12:15], v[226:229], v[192:195], v[12:15]
	v_mfma_f32_16x16x32_bf16 v[4:7], v[218:221], v[200:203], v[4:7]
	v_mfma_f32_16x16x32_bf16 v[0:3], v[226:229], v[200:203], v[0:3]

	s_add_i32 s54, 0, 0x18000

	s_barrier
	ds_read_b128 v[148:151], v143 offset:32768
	ds_read_b128 v[152:155], v143 offset:33792
	ds_read_b128 v[156:159], v143 offset:34816
	ds_read_b128 v[160:163], v143 offset:35840
	s_add_u32 s26, s26, 0x80000
	s_addc_u32 s27, s27, 0
	s_mov_b32 m0, s36

	ds_read_b128 v[164:167], v145 offset:32768
	ds_read_b128 v[176:179], v145 offset:33792
	ds_read_b128 v[180:183], v145 offset:34816
	ds_read_b128 v[184:187], v145 offset:35840
	ds_read_b128 v[188:191], v145 offset:36864
	ds_read_b128 v[192:195], v145 offset:37888
	ds_read_b128 v[196:199], v145 offset:38912
	ds_read_b128 v[200:203], v145 offset:39936
	global_load_lds_dwordx4 v172, s[26:27]
	s_mov_b32 m0, s37
	s_nop 0

	global_load_lds_dwordx4 v174, s[26:27]
	s_waitcnt lgkmcnt(8)
	s_barrier
	s_waitcnt lgkmcnt(0)


	v_mfma_f32_16x16x32_bf16 v[124:127], v[148:151], v[164:167], v[124:127]
	v_mfma_f32_16x16x32_bf16 v[120:123], v[156:159], v[164:167], v[120:123]
	v_mfma_f32_16x16x32_bf16 v[116:119], v[148:151], v[180:183], v[116:119]
	v_mfma_f32_16x16x32_bf16 v[104:107], v[156:159], v[180:183], v[104:107]
	v_mfma_f32_16x16x32_bf16 v[96:99], v[148:151], v[188:191], v[96:99]
	v_mfma_f32_16x16x32_bf16 v[88:91], v[156:159], v[188:191], v[88:91]
	v_mfma_f32_16x16x32_bf16 v[80:83], v[148:151], v[196:199], v[80:83]
	v_mfma_f32_16x16x32_bf16 v[72:75], v[156:159], v[196:199], v[72:75]
	v_mfma_f32_16x16x32_bf16 v[124:127], v[152:155], v[176:179], v[124:127]
	v_mfma_f32_16x16x32_bf16 v[120:123], v[160:163], v[176:179], v[120:123]
	v_mfma_f32_16x16x32_bf16 v[116:119], v[152:155], v[184:187], v[116:119]
	v_mfma_f32_16x16x32_bf16 v[104:107], v[160:163], v[184:187], v[104:107]
	v_mfma_f32_16x16x32_bf16 v[96:99], v[152:155], v[192:195], v[96:99]
	v_mfma_f32_16x16x32_bf16 v[88:91], v[160:163], v[192:195], v[88:91]
	v_mfma_f32_16x16x32_bf16 v[80:83], v[152:155], v[200:203], v[80:83]
	v_mfma_f32_16x16x32_bf16 v[72:75], v[160:163], v[200:203], v[72:75]

	s_barrier
	s_add_i32 s26, 0, 0x1c000
	s_add_i32 s27, s54, s31


	s_mov_b32 m0, s27
	ds_read_b128 v[204:207], v147 offset:32768
	ds_read_b128 v[218:221], v147 offset:33792
	ds_read_b128 v[222:225], v147 offset:34816
	ds_read_b128 v[226:229], v147 offset:35840
	global_load_lds_dwordx4 v172, s[66:67]
	s_add_i32 m0, s27, 0x2000
	s_nop 0

	global_load_lds_dwordx4 v174, s[66:67]
	s_barrier
	s_waitcnt lgkmcnt(0)


	v_mfma_f32_16x16x32_bf16 v[112:115], v[204:207], v[164:167], v[112:115]
	v_mfma_f32_16x16x32_bf16 v[108:111], v[222:225], v[164:167], v[108:111]
	v_mfma_f32_16x16x32_bf16 v[100:103], v[204:207], v[180:183], v[100:103]
	v_mfma_f32_16x16x32_bf16 v[92:95], v[222:225], v[180:183], v[92:95]
	v_mfma_f32_16x16x32_bf16 v[84:87], v[204:207], v[188:191], v[84:87]
	v_mfma_f32_16x16x32_bf16 v[76:79], v[222:225], v[188:191], v[76:79]
	v_mfma_f32_16x16x32_bf16 v[68:71], v[204:207], v[196:199], v[68:71]
	v_mfma_f32_16x16x32_bf16 v[64:67], v[222:225], v[196:199], v[64:67]
	v_mfma_f32_16x16x32_bf16 v[112:115], v[218:221], v[176:179], v[112:115]
	v_mfma_f32_16x16x32_bf16 v[108:111], v[226:229], v[176:179], v[108:111]
	v_mfma_f32_16x16x32_bf16 v[100:103], v[218:221], v[184:187], v[100:103]
	v_mfma_f32_16x16x32_bf16 v[92:95], v[226:229], v[184:187], v[92:95]
	v_mfma_f32_16x16x32_bf16 v[84:87], v[218:221], v[192:195], v[84:87]
	v_mfma_f32_16x16x32_bf16 v[76:79], v[226:229], v[192:195], v[76:79]
	v_mfma_f32_16x16x32_bf16 v[68:71], v[218:221], v[200:203], v[68:71]
	v_mfma_f32_16x16x32_bf16 v[64:67], v[226:229], v[200:203], v[64:67]

	s_mov_b32 m0, s41

	s_barrier
	ds_read_b128 v[164:167], v145 offset:49152
	ds_read_b128 v[176:179], v145 offset:50176
	ds_read_b128 v[180:183], v145 offset:51200
	ds_read_b128 v[184:187], v145 offset:52224
	ds_read_b128 v[188:191], v145 offset:53248
	ds_read_b128 v[192:195], v145 offset:54272
	ds_read_b128 v[196:199], v145 offset:55296
	ds_read_b128 v[200:203], v145 offset:56320
	global_load_lds_dwordx4 v172, s[68:69]
	s_mov_b32 m0, s42
	s_nop 0

	global_load_lds_dwordx4 v174, s[68:69]
	s_barrier
	s_waitcnt lgkmcnt(0)


	v_mfma_f32_16x16x32_bf16 v[60:63], v[148:151], v[164:167], v[60:63]
	v_mfma_f32_16x16x32_bf16 v[56:59], v[156:159], v[164:167], v[56:59]
	v_mfma_f32_16x16x32_bf16 v[48:51], v[148:151], v[180:183], v[48:51]
	v_mfma_f32_16x16x32_bf16 v[40:43], v[156:159], v[180:183], v[40:43]
	v_mfma_f32_16x16x32_bf16 v[32:35], v[148:151], v[188:191], v[32:35]
	v_mfma_f32_16x16x32_bf16 v[24:27], v[156:159], v[188:191], v[24:27]
	v_mfma_f32_16x16x32_bf16 v[16:19], v[148:151], v[196:199], v[16:19]
	v_mfma_f32_16x16x32_bf16 v[8:11], v[156:159], v[196:199], v[8:11]
	v_mfma_f32_16x16x32_bf16 v[60:63], v[152:155], v[176:179], v[60:63]
	v_mfma_f32_16x16x32_bf16 v[56:59], v[160:163], v[176:179], v[56:59]
	v_mfma_f32_16x16x32_bf16 v[48:51], v[152:155], v[184:187], v[48:51]
	v_mfma_f32_16x16x32_bf16 v[40:43], v[160:163], v[184:187], v[40:43]
	v_mfma_f32_16x16x32_bf16 v[32:35], v[152:155], v[192:195], v[32:35]
	v_mfma_f32_16x16x32_bf16 v[24:27], v[160:163], v[192:195], v[24:27]
	v_mfma_f32_16x16x32_bf16 v[16:19], v[152:155], v[200:203], v[16:19]
	v_mfma_f32_16x16x32_bf16 v[8:11], v[160:163], v[200:203], v[8:11]

	s_barrier
	s_add_u32 s24, s24, 0x80080
	s_addc_u32 s25, s25, 0
	s_add_i32 s26, s26, s31
	s_mov_b32 m0, s26
	s_add_i32 s53, s53, 2

	global_load_lds_dwordx4 v172, s[24:25]
	s_add_i32 m0, s26, 0x2000
	s_add_u32 s22, s22, 0x100
	s_addc_u32 s23, s23, 0

	global_load_lds_dwordx4 v174, s[24:25]
	s_add_u32 s51, s51, 0x100
	s_addc_u32 s52, s52, 0
	s_waitcnt vmcnt(6)
	s_barrier

	v_mfma_f32_16x16x32_bf16 v[52:55], v[204:207], v[164:167], v[52:55]
	v_mfma_f32_16x16x32_bf16 v[44:47], v[222:225], v[164:167], v[44:47]
	v_mfma_f32_16x16x32_bf16 v[36:39], v[204:207], v[180:183], v[36:39]
	v_mfma_f32_16x16x32_bf16 v[28:31], v[222:225], v[180:183], v[28:31]
	v_mfma_f32_16x16x32_bf16 v[20:23], v[204:207], v[188:191], v[20:23]
	v_mfma_f32_16x16x32_bf16 v[12:15], v[222:225], v[188:191], v[12:15]
	v_mfma_f32_16x16x32_bf16 v[4:7], v[204:207], v[196:199], v[4:7]
	v_mfma_f32_16x16x32_bf16 v[0:3], v[222:225], v[196:199], v[0:3]
	v_mfma_f32_16x16x32_bf16 v[52:55], v[218:221], v[176:179], v[52:55]
	v_mfma_f32_16x16x32_bf16 v[44:47], v[226:229], v[176:179], v[44:47]
	v_mfma_f32_16x16x32_bf16 v[36:39], v[218:221], v[184:187], v[36:39]
	v_mfma_f32_16x16x32_bf16 v[28:31], v[226:229], v[184:187], v[28:31]
	v_mfma_f32_16x16x32_bf16 v[20:23], v[218:221], v[192:195], v[20:23]
	v_mfma_f32_16x16x32_bf16 v[12:15], v[226:229], v[192:195], v[12:15]
	v_mfma_f32_16x16x32_bf16 v[4:7], v[218:221], v[200:203], v[4:7]
	v_mfma_f32_16x16x32_bf16 v[0:3], v[226:229], v[200:203], v[0:3]


	s_cmp_gt_u32 s53, 29
	s_barrier
	s_cbranch_scc0 .LBB0_1167
	s_lshl_b32 s13, s20, 8
	v_mov_b32_e32 v138, v210
	v_mov_b32_e32 v142, v169
	s_add_i32 s13, s13, s39
	s_lshl_b32 s15, s48, 7
	v_add_u32_e32 v136, s13, v142
	v_ashrrev_i32_e32 v137, 31, v136
	v_lshl_add_u64 v[140:141], v[136:137], 2, s[2:3]
	global_load_dword v154, v[140:141], off
	global_load_dword v152, v[140:141], off offset:64
	v_lshl_add_u32 v138, v138, 4, v142
	v_and_b32_e32 v142, 3, v142
	v_ashrrev_i32_e32 v144, 2, v138
	v_and_b32_e32 v138, -4, v138
	v_lshl_or_b32 v146, v142, 2, s15
	v_add_u32_e32 v151, s13, v144
	v_lshl_add_u32 v149, v142, 6, v138
	v_or_b32_e32 v156, s40, v146
	global_load_dword v150, v[140:141], off offset:128
	global_load_dword v148, v[140:141], off offset:192
	global_load_dword v146, v[140:141], off offset:512
	global_load_dword v144, v[140:141], off offset:576
	global_load_dword v142, v[140:141], off offset:640
	global_load_dword v138, v[140:141], off offset:704
	v_mov_b64_e32 v[136:137], s[0:1]
	v_ashrrev_i32_e32 v157, 31, v156
	v_mad_i64_i32 v[158:159], s[22:23], v151, s47, v[136:137]
	v_lshlrev_b64 v[140:141], 1, v[156:157]
	v_lshl_add_u64 v[156:157], v[158:159], 0, v[140:141]
	v_add_u32_e32 v153, 16, v151
	s_and_b64 vcc, exec, s[4:5]
	s_mov_b32 s48, s12
	s_mov_b32 s20, s14
	s_mov_b64 s[24:25], s[18:19]
	s_waitcnt vmcnt(0)
	v_pk_mul_f32 v[126:127], v[126:127], v[154:155] op_sel_hi:[1,0]
	v_pk_mul_f32 v[124:125], v[124:125], v[154:155] op_sel_hi:[1,0]
	v_pk_mul_f32 v[114:115], v[114:115], v[154:155] op_sel_hi:[1,0]
	v_pk_mul_f32 v[112:113], v[112:113], v[154:155] op_sel_hi:[1,0]
	v_pk_mul_f32 v[122:123], v[122:123], v[154:155] op_sel_hi:[1,0]
	v_pk_mul_f32 v[120:121], v[120:121], v[154:155] op_sel_hi:[1,0]
	v_pk_mul_f32 v[110:111], v[110:111], v[154:155] op_sel_hi:[1,0]
	v_pk_mul_f32 v[108:109], v[108:109], v[154:155] op_sel_hi:[1,0]
	v_mul_f32_e32 v154, 0xbfb8aa3b, v124
	v_mul_f32_e32 v155, 0xbfb8aa3b, v125
	v_mul_f32_e32 v158, 0xbfb8aa3b, v126
	v_mul_f32_e32 v159, 0xbfb8aa3b, v127
	v_mul_f32_e32 v160, 0xbfb8aa3b, v120
	v_mul_f32_e32 v161, 0xbfb8aa3b, v121
	v_mul_f32_e32 v162, 0xbfb8aa3b, v122
	v_mul_f32_e32 v163, 0xbfb8aa3b, v123
	v_exp_f32_e32 v154, v154
	v_exp_f32_e32 v155, v155
	v_exp_f32_e32 v158, v158
	v_exp_f32_e32 v159, v159
	v_exp_f32_e32 v160, v160
	v_exp_f32_e32 v161, v161
	v_exp_f32_e32 v162, v162
	v_exp_f32_e32 v163, v163
	v_add_f32_e32 v154, 1.0, v154
	v_add_f32_e32 v155, 1.0, v155
	v_add_f32_e32 v158, 1.0, v158
	v_add_f32_e32 v159, 1.0, v159
	v_add_f32_e32 v160, 1.0, v160
	v_add_f32_e32 v161, 1.0, v161
	v_add_f32_e32 v162, 1.0, v162
	v_add_f32_e32 v163, 1.0, v163
	v_rcp_f32_e32 v154, v154
	v_rcp_f32_e32 v155, v155
	v_rcp_f32_e32 v158, v158
	v_rcp_f32_e32 v159, v159
	v_rcp_f32_e32 v160, v160
	v_rcp_f32_e32 v161, v161
	v_rcp_f32_e32 v162, v162
	v_rcp_f32_e32 v163, v163
	v_pk_mul_f32 v[124:125], v[124:125], v[154:155]
	v_pk_mul_f32 v[126:127], v[126:127], v[158:159]
	v_pk_mul_f32 v[120:121], v[120:121], v[160:161]
	v_pk_mul_f32 v[122:123], v[122:123], v[162:163]
	v_pk_mul_f32 v[112:113], v[112:113], v[124:125]
	v_pk_mul_f32 v[114:115], v[114:115], v[126:127]
	v_pk_mul_f32 v[118:119], v[118:119], v[152:153] op_sel_hi:[1,0]
	v_pk_mul_f32 v[116:117], v[116:117], v[152:153] op_sel_hi:[1,0]
	v_pk_mul_f32 v[108:109], v[108:109], v[120:121]
	v_pk_mul_f32 v[110:111], v[110:111], v[122:123]
	v_cvt_pk_bf16_f32 v112, v112, v113
	v_cvt_pk_bf16_f32 v113, v114, v115
	v_mul_f32_e32 v164, 0xbfb8aa3b, v116
	v_mul_f32_e32 v165, 0xbfb8aa3b, v117
	v_mul_f32_e32 v166, 0xbfb8aa3b, v118
	v_mul_f32_e32 v167, 0xbfb8aa3b, v119
	v_cvt_pk_bf16_f32 v114, v108, v109
	v_cvt_pk_bf16_f32 v111, v110, v111
	ds_bpermute_b32 v108, v149, v112
	ds_bpermute_b32 v109, v149, v113
	v_exp_f32_e32 v164, v164
	v_exp_f32_e32 v165, v165
	v_exp_f32_e32 v166, v166
	v_exp_f32_e32 v167, v167
	ds_bpermute_b32 v110, v149, v114
	ds_bpermute_b32 v111, v149, v111
	v_add_f32_e32 v164, 1.0, v164
	v_add_f32_e32 v113, 1.0, v165
	s_waitcnt lgkmcnt(0)
	global_store_dwordx2 v[156:157], v[108:109], off
	global_store_dwordx2 v[156:157], v[110:111], off offset:32
	v_add_f32_e32 v108, 1.0, v166
	v_add_f32_e32 v109, 1.0, v167
	v_rcp_f32_e32 v112, v164
	v_rcp_f32_e32 v113, v113
	v_rcp_f32_e32 v108, v108
	v_rcp_f32_e32 v109, v109
	v_pk_mul_f32 v[102:103], v[102:103], v[152:153] op_sel_hi:[1,0]
	v_pk_mul_f32 v[100:101], v[100:101], v[152:153] op_sel_hi:[1,0]
	v_pk_mul_f32 v[110:111], v[116:117], v[112:113]
	v_pk_mul_f32 v[108:109], v[118:119], v[108:109]
	v_pk_mul_f32 v[100:101], v[100:101], v[110:111]
	v_pk_mul_f32 v[102:103], v[102:103], v[108:109]
	v_cvt_pk_bf16_f32 v100, v100, v101
	v_cvt_pk_bf16_f32 v101, v102, v103
	v_pk_mul_f32 v[102:103], v[106:107], v[152:153] op_sel_hi:[1,0]
	v_pk_mul_f32 v[104:105], v[104:105], v[152:153] op_sel_hi:[1,0]
	v_mul_f32_e32 v108, 0xbfb8aa3b, v102
	v_mul_f32_e32 v106, 0xbfb8aa3b, v104
	v_mul_f32_e32 v107, 0xbfb8aa3b, v105
	v_mul_f32_e32 v109, 0xbfb8aa3b, v103
	v_exp_f32_e32 v106, v106
	v_exp_f32_e32 v107, v107
	v_exp_f32_e32 v108, v108
	v_exp_f32_e32 v109, v109
	v_add_f32_e32 v106, 1.0, v106
	v_add_f32_e32 v107, 1.0, v107
	v_add_f32_e32 v108, 1.0, v108
	v_add_f32_e32 v109, 1.0, v109
	v_rcp_f32_e32 v106, v106
	v_rcp_f32_e32 v107, v107
	v_rcp_f32_e32 v108, v108
	v_rcp_f32_e32 v109, v109
	v_pk_mul_f32 v[94:95], v[94:95], v[152:153] op_sel_hi:[1,0]
	v_pk_mul_f32 v[92:93], v[92:93], v[152:153] op_sel_hi:[1,0]
	v_pk_mul_f32 v[104:105], v[104:105], v[106:107]
	v_pk_mul_f32 v[102:103], v[102:103], v[108:109]
	v_pk_mul_f32 v[92:93], v[92:93], v[104:105]
	v_pk_mul_f32 v[94:95], v[94:95], v[102:103]
	ds_bpermute_b32 v100, v149, v100
	ds_bpermute_b32 v101, v149, v101
	v_cvt_pk_bf16_f32 v92, v92, v93
	v_cvt_pk_bf16_f32 v93, v94, v95
	ds_bpermute_b32 v92, v149, v92
	ds_bpermute_b32 v93, v149, v93
	v_mad_i64_i32 v[94:95], s[22:23], v153, s47, v[136:137]
	v_lshl_add_u64 v[94:95], v[94:95], 0, v[140:141]
	s_waitcnt lgkmcnt(2)
	global_store_dwordx2 v[94:95], v[100:101], off
	s_waitcnt lgkmcnt(0)
	global_store_dwordx2 v[94:95], v[92:93], off offset:32
	v_pk_mul_f32 v[92:93], v[98:99], v[150:151] op_sel_hi:[1,0]
	v_pk_mul_f32 v[94:95], v[96:97], v[150:151] op_sel_hi:[1,0]
	v_mul_f32_e32 v98, 0xbfb8aa3b, v92
	v_mul_f32_e32 v96, 0xbfb8aa3b, v94
	v_mul_f32_e32 v97, 0xbfb8aa3b, v95
	v_mul_f32_e32 v99, 0xbfb8aa3b, v93
	v_exp_f32_e32 v96, v96
	v_exp_f32_e32 v97, v97
	v_exp_f32_e32 v98, v98
	v_exp_f32_e32 v99, v99
	v_add_f32_e32 v96, 1.0, v96
	v_add_f32_e32 v97, 1.0, v97
	v_add_f32_e32 v98, 1.0, v98
	v_add_f32_e32 v99, 1.0, v99
	v_rcp_f32_e32 v96, v96
	v_rcp_f32_e32 v97, v97
	v_rcp_f32_e32 v98, v98
	v_rcp_f32_e32 v99, v99
	v_pk_mul_f32 v[86:87], v[86:87], v[150:151] op_sel_hi:[1,0]
	v_pk_mul_f32 v[84:85], v[84:85], v[150:151] op_sel_hi:[1,0]
	v_pk_mul_f32 v[94:95], v[94:95], v[96:97]
	v_pk_mul_f32 v[92:93], v[92:93], v[98:99]
	v_pk_mul_f32 v[84:85], v[84:85], v[94:95]
	v_pk_mul_f32 v[86:87], v[86:87], v[92:93]
	v_cvt_pk_bf16_f32 v84, v84, v85
	v_cvt_pk_bf16_f32 v85, v86, v87
	v_pk_mul_f32 v[86:87], v[90:91], v[150:151] op_sel_hi:[1,0]
	v_pk_mul_f32 v[88:89], v[88:89], v[150:151] op_sel_hi:[1,0]
	v_mul_f32_e32 v92, 0xbfb8aa3b, v86
	v_mul_f32_e32 v90, 0xbfb8aa3b, v88
	v_mul_f32_e32 v91, 0xbfb8aa3b, v89
	v_mul_f32_e32 v93, 0xbfb8aa3b, v87
	v_exp_f32_e32 v90, v90
	v_exp_f32_e32 v91, v91
	v_exp_f32_e32 v92, v92
	v_exp_f32_e32 v93, v93
	v_add_f32_e32 v90, 1.0, v90
	v_add_f32_e32 v91, 1.0, v91
	v_add_f32_e32 v92, 1.0, v92
	v_add_f32_e32 v93, 1.0, v93
	v_rcp_f32_e32 v90, v90
	v_rcp_f32_e32 v91, v91
	v_rcp_f32_e32 v92, v92
	v_rcp_f32_e32 v93, v93
	v_pk_mul_f32 v[78:79], v[78:79], v[150:151] op_sel_hi:[1,0]
	v_pk_mul_f32 v[76:77], v[76:77], v[150:151] op_sel_hi:[1,0]
	v_pk_mul_f32 v[88:89], v[88:89], v[90:91]
	v_pk_mul_f32 v[86:87], v[86:87], v[92:93]
	v_pk_mul_f32 v[76:77], v[76:77], v[88:89]
	v_pk_mul_f32 v[78:79], v[78:79], v[86:87]
	ds_bpermute_b32 v84, v149, v84
	ds_bpermute_b32 v85, v149, v85
	v_cvt_pk_bf16_f32 v76, v76, v77
	v_cvt_pk_bf16_f32 v77, v78, v79
	ds_bpermute_b32 v76, v149, v76
	ds_bpermute_b32 v77, v149, v77
	v_add_u32_e32 v100, 32, v151
	v_mad_i64_i32 v[78:79], s[22:23], v100, s47, v[136:137]
	v_lshl_add_u64 v[78:79], v[78:79], 0, v[140:141]
	s_waitcnt lgkmcnt(2)
	global_store_dwordx2 v[78:79], v[84:85], off
	s_waitcnt lgkmcnt(0)
	global_store_dwordx2 v[78:79], v[76:77], off offset:32
	v_pk_mul_f32 v[76:77], v[82:83], v[148:149] op_sel_hi:[1,0]
	v_pk_mul_f32 v[78:79], v[80:81], v[148:149] op_sel_hi:[1,0]
	v_mul_f32_e32 v82, 0xbfb8aa3b, v76
	v_mul_f32_e32 v80, 0xbfb8aa3b, v78
	v_mul_f32_e32 v81, 0xbfb8aa3b, v79
	v_mul_f32_e32 v83, 0xbfb8aa3b, v77
	v_exp_f32_e32 v80, v80
	v_exp_f32_e32 v81, v81
	v_exp_f32_e32 v82, v82
	v_exp_f32_e32 v83, v83
	v_add_f32_e32 v80, 1.0, v80
	v_add_f32_e32 v81, 1.0, v81
	v_add_f32_e32 v82, 1.0, v82
	v_add_f32_e32 v83, 1.0, v83
	v_rcp_f32_e32 v80, v80
	v_rcp_f32_e32 v81, v81
	v_rcp_f32_e32 v82, v82
	v_rcp_f32_e32 v83, v83
	v_pk_mul_f32 v[70:71], v[70:71], v[148:149] op_sel_hi:[1,0]
	v_pk_mul_f32 v[68:69], v[68:69], v[148:149] op_sel_hi:[1,0]
	v_pk_mul_f32 v[78:79], v[78:79], v[80:81]
	v_pk_mul_f32 v[76:77], v[76:77], v[82:83]
	v_pk_mul_f32 v[68:69], v[68:69], v[78:79]
	v_pk_mul_f32 v[70:71], v[70:71], v[76:77]
	v_cvt_pk_bf16_f32 v68, v68, v69
	v_cvt_pk_bf16_f32 v69, v70, v71
	v_pk_mul_f32 v[70:71], v[74:75], v[148:149] op_sel_hi:[1,0]
	v_pk_mul_f32 v[72:73], v[72:73], v[148:149] op_sel_hi:[1,0]
	v_mul_f32_e32 v76, 0xbfb8aa3b, v70
	v_mul_f32_e32 v74, 0xbfb8aa3b, v72
	v_mul_f32_e32 v75, 0xbfb8aa3b, v73
	v_mul_f32_e32 v77, 0xbfb8aa3b, v71
	v_exp_f32_e32 v74, v74
	v_exp_f32_e32 v75, v75
	v_exp_f32_e32 v76, v76
	v_exp_f32_e32 v77, v77
	v_add_f32_e32 v74, 1.0, v74
	v_add_f32_e32 v75, 1.0, v75
	v_add_f32_e32 v76, 1.0, v76
	v_add_f32_e32 v77, 1.0, v77
	v_rcp_f32_e32 v74, v74
	v_rcp_f32_e32 v75, v75
	v_rcp_f32_e32 v76, v76
	v_rcp_f32_e32 v77, v77
	v_pk_mul_f32 v[66:67], v[66:67], v[148:149] op_sel_hi:[1,0]
	v_pk_mul_f32 v[64:65], v[64:65], v[148:149] op_sel_hi:[1,0]
	v_pk_mul_f32 v[72:73], v[72:73], v[74:75]
	v_pk_mul_f32 v[70:71], v[70:71], v[76:77]
	v_pk_mul_f32 v[64:65], v[64:65], v[72:73]
	v_pk_mul_f32 v[66:67], v[66:67], v[70:71]
	ds_bpermute_b32 v68, v149, v68
	ds_bpermute_b32 v69, v149, v69
	v_cvt_pk_bf16_f32 v64, v64, v65
	v_cvt_pk_bf16_f32 v65, v66, v67
	ds_bpermute_b32 v64, v149, v64
	ds_bpermute_b32 v65, v149, v65
	v_add_u32_e32 v84, 48, v151
	v_mad_i64_i32 v[66:67], s[22:23], v84, s47, v[136:137]
	v_lshl_add_u64 v[66:67], v[66:67], 0, v[140:141]
	v_pk_mul_f32 v[60:61], v[60:61], v[146:147] op_sel_hi:[1,0]
	s_waitcnt lgkmcnt(2)
	global_store_dwordx2 v[66:67], v[68:69], off
	s_waitcnt lgkmcnt(0)
	global_store_dwordx2 v[66:67], v[64:65], off offset:32
	v_pk_mul_f32 v[62:63], v[62:63], v[146:147] op_sel_hi:[1,0]
	v_mul_f32_e32 v64, 0xbfb8aa3b, v60
	v_mul_f32_e32 v65, 0xbfb8aa3b, v61
	v_exp_f32_e32 v64, v64
	v_exp_f32_e32 v65, v65
	v_mul_f32_e32 v66, 0xbfb8aa3b, v62
	v_mul_f32_e32 v67, 0xbfb8aa3b, v63
	v_exp_f32_e32 v66, v66
	v_exp_f32_e32 v67, v67
	v_add_f32_e32 v64, 1.0, v64
	v_add_f32_e32 v65, 1.0, v65
	v_rcp_f32_e32 v64, v64
	v_rcp_f32_e32 v65, v65
	v_add_f32_e32 v66, 1.0, v66
	v_add_f32_e32 v67, 1.0, v67
	v_rcp_f32_e32 v66, v66
	v_rcp_f32_e32 v67, v67
	v_pk_mul_f32 v[52:53], v[52:53], v[146:147] op_sel_hi:[1,0]
	v_pk_mul_f32 v[60:61], v[60:61], v[64:65]
	v_pk_mul_f32 v[54:55], v[54:55], v[146:147] op_sel_hi:[1,0]
	v_pk_mul_f32 v[52:53], v[52:53], v[60:61]
	v_pk_mul_f32 v[60:61], v[62:63], v[66:67]
	v_cvt_pk_bf16_f32 v52, v52, v53
	v_pk_mul_f32 v[54:55], v[54:55], v[60:61]
	v_pk_mul_f32 v[56:57], v[56:57], v[146:147] op_sel_hi:[1,0]
	v_cvt_pk_bf16_f32 v53, v54, v55
	v_pk_mul_f32 v[54:55], v[58:59], v[146:147] op_sel_hi:[1,0]
	v_mul_f32_e32 v58, 0xbfb8aa3b, v56
	v_mul_f32_e32 v59, 0xbfb8aa3b, v57
	v_mul_f32_e32 v60, 0xbfb8aa3b, v54
	v_mul_f32_e32 v61, 0xbfb8aa3b, v55
	v_exp_f32_e32 v58, v58
	v_exp_f32_e32 v59, v59
	v_exp_f32_e32 v60, v60
	v_exp_f32_e32 v61, v61
	v_add_f32_e32 v58, 1.0, v58
	v_add_f32_e32 v59, 1.0, v59
	v_add_f32_e32 v60, 1.0, v60
	v_add_f32_e32 v61, 1.0, v61
	v_rcp_f32_e32 v58, v58
	v_rcp_f32_e32 v59, v59
	v_rcp_f32_e32 v60, v60
	v_rcp_f32_e32 v61, v61
	v_pk_mul_f32 v[46:47], v[46:47], v[146:147] op_sel_hi:[1,0]
	v_pk_mul_f32 v[44:45], v[44:45], v[146:147] op_sel_hi:[1,0]
	v_pk_mul_f32 v[56:57], v[56:57], v[58:59]
	v_pk_mul_f32 v[54:55], v[54:55], v[60:61]
	v_pk_mul_f32 v[44:45], v[44:45], v[56:57]
	v_pk_mul_f32 v[46:47], v[46:47], v[54:55]
	ds_bpermute_b32 v52, v149, v52
	ds_bpermute_b32 v53, v149, v53
	v_cvt_pk_bf16_f32 v44, v44, v45
	v_cvt_pk_bf16_f32 v45, v46, v47
	ds_bpermute_b32 v44, v149, v44
	ds_bpermute_b32 v45, v149, v45
	v_add_u32_e32 v68, 0x80, v151
	v_mad_i64_i32 v[46:47], s[22:23], v68, s47, v[136:137]
	v_lshl_add_u64 v[46:47], v[46:47], 0, v[140:141]
	s_waitcnt lgkmcnt(2)
	global_store_dwordx2 v[46:47], v[52:53], off
	s_waitcnt lgkmcnt(0)
	global_store_dwordx2 v[46:47], v[44:45], off offset:32
	v_pk_mul_f32 v[44:45], v[50:51], v[144:145] op_sel_hi:[1,0]
	v_pk_mul_f32 v[46:47], v[48:49], v[144:145] op_sel_hi:[1,0]
	v_mul_f32_e32 v50, 0xbfb8aa3b, v44
	v_mul_f32_e32 v48, 0xbfb8aa3b, v46
	v_mul_f32_e32 v49, 0xbfb8aa3b, v47
	v_mul_f32_e32 v51, 0xbfb8aa3b, v45
	v_exp_f32_e32 v48, v48
	v_exp_f32_e32 v49, v49
	v_exp_f32_e32 v50, v50
	v_exp_f32_e32 v51, v51
	v_add_f32_e32 v48, 1.0, v48
	v_add_f32_e32 v49, 1.0, v49
	v_add_f32_e32 v50, 1.0, v50
	v_add_f32_e32 v51, 1.0, v51
	v_rcp_f32_e32 v48, v48
	v_rcp_f32_e32 v49, v49
	v_rcp_f32_e32 v50, v50
	v_rcp_f32_e32 v51, v51
	v_pk_mul_f32 v[38:39], v[38:39], v[144:145] op_sel_hi:[1,0]
	v_pk_mul_f32 v[36:37], v[36:37], v[144:145] op_sel_hi:[1,0]
	v_pk_mul_f32 v[46:47], v[46:47], v[48:49]
	v_pk_mul_f32 v[44:45], v[44:45], v[50:51]
	v_pk_mul_f32 v[36:37], v[36:37], v[46:47]
	v_pk_mul_f32 v[38:39], v[38:39], v[44:45]
	v_cvt_pk_bf16_f32 v36, v36, v37
	v_cvt_pk_bf16_f32 v37, v38, v39
	v_pk_mul_f32 v[38:39], v[42:43], v[144:145] op_sel_hi:[1,0]
	v_pk_mul_f32 v[40:41], v[40:41], v[144:145] op_sel_hi:[1,0]
	v_mul_f32_e32 v44, 0xbfb8aa3b, v38
	v_mul_f32_e32 v42, 0xbfb8aa3b, v40
	v_mul_f32_e32 v43, 0xbfb8aa3b, v41
	v_mul_f32_e32 v45, 0xbfb8aa3b, v39
	v_exp_f32_e32 v42, v42
	v_exp_f32_e32 v43, v43
	v_exp_f32_e32 v44, v44
	v_exp_f32_e32 v45, v45
	v_add_f32_e32 v42, 1.0, v42
	v_add_f32_e32 v43, 1.0, v43
	v_add_f32_e32 v44, 1.0, v44
	v_add_f32_e32 v45, 1.0, v45
	v_rcp_f32_e32 v42, v42
	v_rcp_f32_e32 v43, v43
	v_rcp_f32_e32 v44, v44
	v_rcp_f32_e32 v45, v45
	v_pk_mul_f32 v[30:31], v[30:31], v[144:145] op_sel_hi:[1,0]
	v_pk_mul_f32 v[28:29], v[28:29], v[144:145] op_sel_hi:[1,0]
	v_pk_mul_f32 v[40:41], v[40:41], v[42:43]
	v_pk_mul_f32 v[38:39], v[38:39], v[44:45]
	v_pk_mul_f32 v[28:29], v[28:29], v[40:41]
	v_pk_mul_f32 v[30:31], v[30:31], v[38:39]
	ds_bpermute_b32 v36, v149, v36
	ds_bpermute_b32 v37, v149, v37
	v_cvt_pk_bf16_f32 v28, v28, v29
	v_cvt_pk_bf16_f32 v29, v30, v31
	ds_bpermute_b32 v28, v149, v28
	ds_bpermute_b32 v29, v149, v29
	v_add_u32_e32 v52, 0x90, v151
	v_mad_i64_i32 v[30:31], s[22:23], v52, s47, v[136:137]
	v_lshl_add_u64 v[30:31], v[30:31], 0, v[140:141]
	s_waitcnt lgkmcnt(2)
	global_store_dwordx2 v[30:31], v[36:37], off
	s_waitcnt lgkmcnt(0)
	global_store_dwordx2 v[30:31], v[28:29], off offset:32
	v_pk_mul_f32 v[28:29], v[34:35], v[142:143] op_sel_hi:[1,0]
	v_pk_mul_f32 v[30:31], v[32:33], v[142:143] op_sel_hi:[1,0]
	v_mul_f32_e32 v34, 0xbfb8aa3b, v28
	v_mul_f32_e32 v32, 0xbfb8aa3b, v30
	v_mul_f32_e32 v33, 0xbfb8aa3b, v31
	v_mul_f32_e32 v35, 0xbfb8aa3b, v29
	v_exp_f32_e32 v32, v32
	v_exp_f32_e32 v33, v33
	v_exp_f32_e32 v34, v34
	v_exp_f32_e32 v35, v35
	v_add_f32_e32 v32, 1.0, v32
	v_add_f32_e32 v33, 1.0, v33
	v_add_f32_e32 v34, 1.0, v34
	v_add_f32_e32 v35, 1.0, v35
	v_rcp_f32_e32 v32, v32
	v_rcp_f32_e32 v33, v33
	v_rcp_f32_e32 v34, v34
	v_rcp_f32_e32 v35, v35
	v_pk_mul_f32 v[22:23], v[22:23], v[142:143] op_sel_hi:[1,0]
	v_pk_mul_f32 v[20:21], v[20:21], v[142:143] op_sel_hi:[1,0]
	v_pk_mul_f32 v[30:31], v[30:31], v[32:33]
	v_pk_mul_f32 v[28:29], v[28:29], v[34:35]
	v_pk_mul_f32 v[20:21], v[20:21], v[30:31]
	v_pk_mul_f32 v[22:23], v[22:23], v[28:29]
	v_cvt_pk_bf16_f32 v20, v20, v21
	v_cvt_pk_bf16_f32 v21, v22, v23
	v_pk_mul_f32 v[22:23], v[26:27], v[142:143] op_sel_hi:[1,0]
	v_pk_mul_f32 v[24:25], v[24:25], v[142:143] op_sel_hi:[1,0]
	v_mul_f32_e32 v28, 0xbfb8aa3b, v22
	v_mul_f32_e32 v26, 0xbfb8aa3b, v24
	v_mul_f32_e32 v27, 0xbfb8aa3b, v25
	v_mul_f32_e32 v29, 0xbfb8aa3b, v23
	v_exp_f32_e32 v26, v26
	v_exp_f32_e32 v27, v27
	v_exp_f32_e32 v28, v28
	v_exp_f32_e32 v29, v29
	v_add_f32_e32 v26, 1.0, v26
	v_add_f32_e32 v27, 1.0, v27
	v_add_f32_e32 v28, 1.0, v28
	v_add_f32_e32 v29, 1.0, v29
	v_rcp_f32_e32 v26, v26
	v_rcp_f32_e32 v27, v27
	v_rcp_f32_e32 v28, v28
	v_rcp_f32_e32 v29, v29
	v_pk_mul_f32 v[14:15], v[14:15], v[142:143] op_sel_hi:[1,0]
	v_pk_mul_f32 v[12:13], v[12:13], v[142:143] op_sel_hi:[1,0]
	v_pk_mul_f32 v[24:25], v[24:25], v[26:27]
	v_pk_mul_f32 v[22:23], v[22:23], v[28:29]
	v_pk_mul_f32 v[12:13], v[12:13], v[24:25]
	v_pk_mul_f32 v[14:15], v[14:15], v[22:23]
	ds_bpermute_b32 v20, v149, v20
	ds_bpermute_b32 v21, v149, v21
	v_cvt_pk_bf16_f32 v12, v12, v13
	v_cvt_pk_bf16_f32 v13, v14, v15
	ds_bpermute_b32 v12, v149, v12
	ds_bpermute_b32 v13, v149, v13
	v_add_u32_e32 v36, 0xa0, v151
	v_mad_i64_i32 v[14:15], s[22:23], v36, s47, v[136:137]
	v_lshl_add_u64 v[14:15], v[14:15], 0, v[140:141]
	s_waitcnt lgkmcnt(2)
	global_store_dwordx2 v[14:15], v[20:21], off
	s_waitcnt lgkmcnt(0)
	global_store_dwordx2 v[14:15], v[12:13], off offset:32
	v_pk_mul_f32 v[12:13], v[18:19], v[138:139] op_sel_hi:[1,0]
	v_pk_mul_f32 v[14:15], v[16:17], v[138:139] op_sel_hi:[1,0]
	v_mul_f32_e32 v18, 0xbfb8aa3b, v12
	v_mul_f32_e32 v16, 0xbfb8aa3b, v14
	v_mul_f32_e32 v17, 0xbfb8aa3b, v15
	v_mul_f32_e32 v19, 0xbfb8aa3b, v13
	v_exp_f32_e32 v16, v16
	v_exp_f32_e32 v17, v17
	v_exp_f32_e32 v18, v18
	v_exp_f32_e32 v19, v19
	v_add_f32_e32 v16, 1.0, v16
	v_add_f32_e32 v17, 1.0, v17
	v_add_f32_e32 v18, 1.0, v18
	v_add_f32_e32 v19, 1.0, v19
	v_rcp_f32_e32 v16, v16
	v_rcp_f32_e32 v17, v17
	v_rcp_f32_e32 v18, v18
	v_rcp_f32_e32 v19, v19
	v_pk_mul_f32 v[6:7], v[6:7], v[138:139] op_sel_hi:[1,0]
	v_pk_mul_f32 v[4:5], v[4:5], v[138:139] op_sel_hi:[1,0]
	v_pk_mul_f32 v[14:15], v[14:15], v[16:17]
	v_pk_mul_f32 v[12:13], v[12:13], v[18:19]
	v_pk_mul_f32 v[4:5], v[4:5], v[14:15]
	v_pk_mul_f32 v[6:7], v[6:7], v[12:13]
	v_cvt_pk_bf16_f32 v4, v4, v5
	v_cvt_pk_bf16_f32 v5, v6, v7
	v_pk_mul_f32 v[6:7], v[10:11], v[138:139] op_sel_hi:[1,0]
	v_pk_mul_f32 v[8:9], v[8:9], v[138:139] op_sel_hi:[1,0]
	v_mul_f32_e32 v12, 0xbfb8aa3b, v6
	v_mul_f32_e32 v10, 0xbfb8aa3b, v8
	v_mul_f32_e32 v11, 0xbfb8aa3b, v9
	v_mul_f32_e32 v13, 0xbfb8aa3b, v7
	v_exp_f32_e32 v10, v10
	v_exp_f32_e32 v11, v11
	v_exp_f32_e32 v12, v12
	v_exp_f32_e32 v13, v13
	v_add_f32_e32 v10, 1.0, v10
	v_add_f32_e32 v11, 1.0, v11
	v_add_f32_e32 v12, 1.0, v12
	v_add_f32_e32 v13, 1.0, v13
	v_rcp_f32_e32 v10, v10
	v_rcp_f32_e32 v11, v11
	v_rcp_f32_e32 v12, v12
	v_rcp_f32_e32 v13, v13
	v_pk_mul_f32 v[2:3], v[2:3], v[138:139] op_sel_hi:[1,0]
	v_pk_mul_f32 v[0:1], v[0:1], v[138:139] op_sel_hi:[1,0]
	v_pk_mul_f32 v[8:9], v[8:9], v[10:11]
	v_pk_mul_f32 v[6:7], v[6:7], v[12:13]
	v_pk_mul_f32 v[0:1], v[0:1], v[8:9]
	v_pk_mul_f32 v[2:3], v[2:3], v[6:7]
	ds_bpermute_b32 v4, v149, v4
	ds_bpermute_b32 v5, v149, v5
	v_cvt_pk_bf16_f32 v0, v0, v1
	v_cvt_pk_bf16_f32 v1, v2, v3
	ds_bpermute_b32 v0, v149, v0
	ds_bpermute_b32 v1, v149, v1
	v_add_u32_e32 v20, 0xb0, v151
	v_mad_i64_i32 v[2:3], s[22:23], v20, s47, v[136:137]
	v_lshl_add_u64 v[2:3], v[2:3], 0, v[140:141]
	s_mov_b64 s[22:23], s[16:17]
	s_waitcnt lgkmcnt(2)
	global_store_dwordx2 v[2:3], v[4:5], off
	s_waitcnt lgkmcnt(0)
	global_store_dwordx2 v[2:3], v[0:1], off offset:32
	s_cbranch_vccz .LBB0_1164
	s_waitcnt vmcnt(0)
	s_cmpk_gt_u32 s28, 0xff
	s_cbranch_scc1 .LBB0_1171
	s_barrier

.LBB0_1258:
	ds_read_b128 v[128:131], v159
	ds_read_b128 v[132:135], v159 offset:1024
	ds_read_b128 v[136:139], v159 offset:2048
	ds_read_b128 v[150:153], v159 offset:3072


	s_add_i32 m0, s26, 0xc000
	ds_read_b128 v[154:157], v160
	ds_read_b128 v[162:165], v160 offset:1024
	ds_read_b128 v[172:175], v160 offset:2048
	ds_read_b128 v[176:179], v160 offset:3072
	ds_read_b128 v[180:183], v160 offset:4096
	ds_read_b128 v[184:187], v160 offset:5120
	ds_read_b128 v[188:191], v160 offset:6144
	ds_read_b128 v[192:195], v160 offset:7168
	global_load_lds_dwordx4 v146, s[16:17]
	s_add_i32 m0, s26, 0xe000
	s_nop 0

	global_load_lds_dwordx4 v148, s[16:17]
	s_add_i32 s54, s18, 2
	s_add_u32 s19, s16, 0xffea0080
	s_addc_u32 s20, s17, -1
	s_cmp_eq_u32 s13, s18
	s_cselect_b32 s18, s4, s52
	s_cselect_b32 s21, s15, s20
	s_cselect_b32 s20, s14, s19
	s_cselect_b32 s19, s5, s53
	s_waitcnt lgkmcnt(8)
	s_barrier
	s_waitcnt lgkmcnt(0)


	v_mfma_f32_16x16x32_bf16 v[124:127], v[128:131], v[154:157], v[124:127]
	v_mfma_f32_16x16x32_bf16 v[120:123], v[136:139], v[154:157], v[120:123]
	v_mfma_f32_16x16x32_bf16 v[116:119], v[128:131], v[172:175], v[116:119]
	v_mfma_f32_16x16x32_bf16 v[104:107], v[136:139], v[172:175], v[104:107]
	v_mfma_f32_16x16x32_bf16 v[96:99], v[128:131], v[180:183], v[96:99]
	v_mfma_f32_16x16x32_bf16 v[88:91], v[136:139], v[180:183], v[88:91]
	v_mfma_f32_16x16x32_bf16 v[80:83], v[128:131], v[188:191], v[80:83]
	v_mfma_f32_16x16x32_bf16 v[72:75], v[136:139], v[188:191], v[72:75]
	v_mfma_f32_16x16x32_bf16 v[124:127], v[132:135], v[162:165], v[124:127]
	v_mfma_f32_16x16x32_bf16 v[120:123], v[150:153], v[162:165], v[120:123]
	v_mfma_f32_16x16x32_bf16 v[116:119], v[132:135], v[176:179], v[116:119]
	v_mfma_f32_16x16x32_bf16 v[104:107], v[150:153], v[176:179], v[104:107]
	v_mfma_f32_16x16x32_bf16 v[96:99], v[132:135], v[184:187], v[96:99]
	v_mfma_f32_16x16x32_bf16 v[88:91], v[150:153], v[184:187], v[88:91]
	v_mfma_f32_16x16x32_bf16 v[80:83], v[132:135], v[192:195], v[80:83]
	v_mfma_f32_16x16x32_bf16 v[72:75], v[150:153], v[192:195], v[72:75]

	s_barrier
	s_add_i32 s55, s35, s25
	s_add_u32 s66, s18, s6
	s_addc_u32 s67, s19, s7
	s_mov_b32 m0, s55
	ds_read_b128 v[196:199], v161
	ds_read_b128 v[200:203], v161 offset:1024
	ds_read_b128 v[204:207], v161 offset:2048
	ds_read_b128 v[212:215], v161 offset:3072
	global_load_lds_dwordx4 v140, s[18:19]
	s_add_i32 m0, s55, 0x2000
	s_nop 0

	global_load_lds_dwordx4 v142, s[18:19]
	s_barrier
	s_waitcnt lgkmcnt(0)


	v_mfma_f32_16x16x32_bf16 v[112:115], v[196:199], v[154:157], v[112:115]
	v_mfma_f32_16x16x32_bf16 v[108:111], v[204:207], v[154:157], v[108:111]
	v_mfma_f32_16x16x32_bf16 v[100:103], v[196:199], v[172:175], v[100:103]
	v_mfma_f32_16x16x32_bf16 v[92:95], v[204:207], v[172:175], v[92:95]
	v_mfma_f32_16x16x32_bf16 v[84:87], v[196:199], v[180:183], v[84:87]
	v_mfma_f32_16x16x32_bf16 v[76:79], v[204:207], v[180:183], v[76:79]
	v_mfma_f32_16x16x32_bf16 v[68:71], v[196:199], v[188:191], v[68:71]
	v_mfma_f32_16x16x32_bf16 v[64:67], v[204:207], v[188:191], v[64:67]
	v_mfma_f32_16x16x32_bf16 v[112:115], v[200:203], v[162:165], v[112:115]
	v_mfma_f32_16x16x32_bf16 v[108:111], v[212:215], v[162:165], v[108:111]
	v_mfma_f32_16x16x32_bf16 v[100:103], v[200:203], v[176:179], v[100:103]
	v_mfma_f32_16x16x32_bf16 v[92:95], v[212:215], v[176:179], v[92:95]
	v_mfma_f32_16x16x32_bf16 v[84:87], v[200:203], v[184:187], v[84:87]
	v_mfma_f32_16x16x32_bf16 v[76:79], v[212:215], v[184:187], v[76:79]
	v_mfma_f32_16x16x32_bf16 v[68:71], v[200:203], v[192:195], v[68:71]
	v_mfma_f32_16x16x32_bf16 v[64:67], v[212:215], v[192:195], v[64:67]

	s_mov_b32 m0, s26
	s_add_u32 s68, s20, s6
	s_addc_u32 s69, s21, s7
	s_barrier
	ds_read_b128 v[154:157], v160 offset:16384
	ds_read_b128 v[162:165], v160 offset:17408
	ds_read_b128 v[172:175], v160 offset:18432
	ds_read_b128 v[176:179], v160 offset:19456
	ds_read_b128 v[180:183], v160 offset:20480
	ds_read_b128 v[184:187], v160 offset:21504
	ds_read_b128 v[188:191], v160 offset:22528
	ds_read_b128 v[192:195], v160 offset:23552
	global_load_lds_dwordx4 v140, s[20:21]
	s_mov_b32 m0, s27
	s_nop 0

	global_load_lds_dwordx4 v142, s[20:21]
	s_barrier
	s_waitcnt lgkmcnt(0)


	v_mfma_f32_16x16x32_bf16 v[60:63], v[128:131], v[154:157], v[60:63]
	v_mfma_f32_16x16x32_bf16 v[56:59], v[136:139], v[154:157], v[56:59]
	v_mfma_f32_16x16x32_bf16 v[52:55], v[128:131], v[172:175], v[52:55]
	v_mfma_f32_16x16x32_bf16 v[40:43], v[136:139], v[172:175], v[40:43]
	v_mfma_f32_16x16x32_bf16 v[36:39], v[128:131], v[180:183], v[36:39]
	v_mfma_f32_16x16x32_bf16 v[24:27], v[136:139], v[180:183], v[24:27]
	v_mfma_f32_16x16x32_bf16 v[20:23], v[128:131], v[188:191], v[20:23]
	v_mfma_f32_16x16x32_bf16 v[8:11], v[136:139], v[188:191], v[8:11]
	v_mfma_f32_16x16x32_bf16 v[60:63], v[132:135], v[162:165], v[60:63]
	v_mfma_f32_16x16x32_bf16 v[56:59], v[150:153], v[162:165], v[56:59]
	v_mfma_f32_16x16x32_bf16 v[52:55], v[132:135], v[176:179], v[52:55]
	v_mfma_f32_16x16x32_bf16 v[40:43], v[150:153], v[176:179], v[40:43]
	v_mfma_f32_16x16x32_bf16 v[36:39], v[132:135], v[184:187], v[36:39]
	v_mfma_f32_16x16x32_bf16 v[24:27], v[150:153], v[184:187], v[24:27]
	v_mfma_f32_16x16x32_bf16 v[20:23], v[132:135], v[192:195], v[20:23]
	v_mfma_f32_16x16x32_bf16 v[8:11], v[150:153], v[192:195], v[8:11]

	s_barrier
	s_add_u32 s56, s18, 0x160000
	s_addc_u32 s57, s19, 0
	s_add_i32 s55, s36, s25
	s_mov_b32 m0, s55
	s_nop 0

	global_load_lds_dwordx4 v140, s[56:57]
	s_add_i32 m0, s55, 0x2000
	s_nop 0

	global_load_lds_dwordx4 v142, s[56:57]
	s_waitcnt vmcnt(6)
	s_barrier

	v_mfma_f32_16x16x32_bf16 v[48:51], v[196:199], v[154:157], v[48:51]
	v_mfma_f32_16x16x32_bf16 v[44:47], v[204:207], v[154:157], v[44:47]
	v_mfma_f32_16x16x32_bf16 v[32:35], v[196:199], v[172:175], v[32:35]
	v_mfma_f32_16x16x32_bf16 v[28:31], v[204:207], v[172:175], v[28:31]
	v_mfma_f32_16x16x32_bf16 v[16:19], v[196:199], v[180:183], v[16:19]
	v_mfma_f32_16x16x32_bf16 v[12:15], v[204:207], v[180:183], v[12:15]
	v_mfma_f32_16x16x32_bf16 v[4:7], v[196:199], v[188:191], v[4:7]
	v_mfma_f32_16x16x32_bf16 v[0:3], v[204:207], v[188:191], v[0:3]
	v_mfma_f32_16x16x32_bf16 v[48:51], v[200:203], v[162:165], v[48:51]
	v_mfma_f32_16x16x32_bf16 v[44:47], v[212:215], v[162:165], v[44:47]
	v_mfma_f32_16x16x32_bf16 v[32:35], v[200:203], v[176:179], v[32:35]
	v_mfma_f32_16x16x32_bf16 v[28:31], v[212:215], v[176:179], v[28:31]
	v_mfma_f32_16x16x32_bf16 v[16:19], v[200:203], v[184:187], v[16:19]
	v_mfma_f32_16x16x32_bf16 v[12:15], v[212:215], v[184:187], v[12:15]
	v_mfma_f32_16x16x32_bf16 v[4:7], v[200:203], v[192:195], v[4:7]
	v_mfma_f32_16x16x32_bf16 v[0:3], v[212:215], v[192:195], v[0:3]

	s_add_i32 s55, 0, 0x18000

	s_barrier
	ds_read_b128 v[128:131], v159 offset:32768
	ds_read_b128 v[132:135], v159 offset:33792
	ds_read_b128 v[136:139], v159 offset:34816
	ds_read_b128 v[150:153], v159 offset:35840
	s_add_u32 s20, s20, 0x160000
	s_addc_u32 s21, s21, 0
	s_mov_b32 m0, s28

	ds_read_b128 v[154:157], v160 offset:32768
	ds_read_b128 v[162:165], v160 offset:33792
	ds_read_b128 v[172:175], v160 offset:34816
	ds_read_b128 v[176:179], v160 offset:35840
	ds_read_b128 v[180:183], v160 offset:36864
	ds_read_b128 v[184:187], v160 offset:37888
	ds_read_b128 v[188:191], v160 offset:38912
	ds_read_b128 v[192:195], v160 offset:39936
	global_load_lds_dwordx4 v140, s[20:21]
	s_mov_b32 m0, s29
	s_nop 0

	global_load_lds_dwordx4 v142, s[20:21]
	s_waitcnt lgkmcnt(8)
	s_barrier
	s_waitcnt lgkmcnt(0)


	v_mfma_f32_16x16x32_bf16 v[124:127], v[128:131], v[154:157], v[124:127]
	v_mfma_f32_16x16x32_bf16 v[120:123], v[136:139], v[154:157], v[120:123]
	v_mfma_f32_16x16x32_bf16 v[116:119], v[128:131], v[172:175], v[116:119]
	v_mfma_f32_16x16x32_bf16 v[104:107], v[136:139], v[172:175], v[104:107]
	v_mfma_f32_16x16x32_bf16 v[96:99], v[128:131], v[180:183], v[96:99]
	v_mfma_f32_16x16x32_bf16 v[88:91], v[136:139], v[180:183], v[88:91]
	v_mfma_f32_16x16x32_bf16 v[80:83], v[128:131], v[188:191], v[80:83]
	v_mfma_f32_16x16x32_bf16 v[72:75], v[136:139], v[188:191], v[72:75]
	v_mfma_f32_16x16x32_bf16 v[124:127], v[132:135], v[162:165], v[124:127]
	v_mfma_f32_16x16x32_bf16 v[120:123], v[150:153], v[162:165], v[120:123]
	v_mfma_f32_16x16x32_bf16 v[116:119], v[132:135], v[176:179], v[116:119]
	v_mfma_f32_16x16x32_bf16 v[104:107], v[150:153], v[176:179], v[104:107]
	v_mfma_f32_16x16x32_bf16 v[96:99], v[132:135], v[184:187], v[96:99]
	v_mfma_f32_16x16x32_bf16 v[88:91], v[150:153], v[184:187], v[88:91]
	v_mfma_f32_16x16x32_bf16 v[80:83], v[132:135], v[192:195], v[80:83]
	v_mfma_f32_16x16x32_bf16 v[72:75], v[150:153], v[192:195], v[72:75]

	s_barrier
	s_add_i32 s20, 0, 0x1c000
	s_add_i32 s21, s55, s25


	s_mov_b32 m0, s21
	ds_read_b128 v[196:199], v161 offset:32768
	ds_read_b128 v[200:203], v161 offset:33792
	ds_read_b128 v[204:207], v161 offset:34816
	ds_read_b128 v[212:215], v161 offset:35840
	global_load_lds_dwordx4 v140, s[66:67]
	s_add_i32 m0, s21, 0x2000
	s_nop 0

	global_load_lds_dwordx4 v142, s[66:67]
	s_barrier
	s_waitcnt lgkmcnt(0)


	v_mfma_f32_16x16x32_bf16 v[112:115], v[196:199], v[154:157], v[112:115]
	v_mfma_f32_16x16x32_bf16 v[108:111], v[204:207], v[154:157], v[108:111]
	v_mfma_f32_16x16x32_bf16 v[100:103], v[196:199], v[172:175], v[100:103]
	v_mfma_f32_16x16x32_bf16 v[92:95], v[204:207], v[172:175], v[92:95]
	v_mfma_f32_16x16x32_bf16 v[84:87], v[196:199], v[180:183], v[84:87]
	v_mfma_f32_16x16x32_bf16 v[76:79], v[204:207], v[180:183], v[76:79]
	v_mfma_f32_16x16x32_bf16 v[68:71], v[196:199], v[188:191], v[68:71]
	v_mfma_f32_16x16x32_bf16 v[64:67], v[204:207], v[188:191], v[64:67]
	v_mfma_f32_16x16x32_bf16 v[112:115], v[200:203], v[162:165], v[112:115]
	v_mfma_f32_16x16x32_bf16 v[108:111], v[212:215], v[162:165], v[108:111]
	v_mfma_f32_16x16x32_bf16 v[100:103], v[200:203], v[176:179], v[100:103]
	v_mfma_f32_16x16x32_bf16 v[92:95], v[212:215], v[176:179], v[92:95]
	v_mfma_f32_16x16x32_bf16 v[84:87], v[200:203], v[184:187], v[84:87]
	v_mfma_f32_16x16x32_bf16 v[76:79], v[212:215], v[184:187], v[76:79]
	v_mfma_f32_16x16x32_bf16 v[68:71], v[200:203], v[192:195], v[68:71]
	v_mfma_f32_16x16x32_bf16 v[64:67], v[212:215], v[192:195], v[64:67]

	s_mov_b32 m0, s33

	s_barrier
	ds_read_b128 v[154:157], v160 offset:49152
	ds_read_b128 v[162:165], v160 offset:50176
	ds_read_b128 v[172:175], v160 offset:51200
	ds_read_b128 v[176:179], v160 offset:52224
	ds_read_b128 v[180:183], v160 offset:53248
	ds_read_b128 v[184:187], v160 offset:54272
	ds_read_b128 v[188:191], v160 offset:55296
	ds_read_b128 v[192:195], v160 offset:56320
	global_load_lds_dwordx4 v140, s[68:69]
	s_mov_b32 m0, s34
	s_nop 0

	global_load_lds_dwordx4 v142, s[68:69]
	s_barrier
	s_waitcnt lgkmcnt(0)


	v_mfma_f32_16x16x32_bf16 v[60:63], v[128:131], v[154:157], v[60:63]
	v_mfma_f32_16x16x32_bf16 v[56:59], v[136:139], v[154:157], v[56:59]
	v_mfma_f32_16x16x32_bf16 v[52:55], v[128:131], v[172:175], v[52:55]
	v_mfma_f32_16x16x32_bf16 v[40:43], v[136:139], v[172:175], v[40:43]
	v_mfma_f32_16x16x32_bf16 v[36:39], v[128:131], v[180:183], v[36:39]
	v_mfma_f32_16x16x32_bf16 v[24:27], v[136:139], v[180:183], v[24:27]
	v_mfma_f32_16x16x32_bf16 v[20:23], v[128:131], v[188:191], v[20:23]
	v_mfma_f32_16x16x32_bf16 v[8:11], v[136:139], v[188:191], v[8:11]
	v_mfma_f32_16x16x32_bf16 v[60:63], v[132:135], v[162:165], v[60:63]
	v_mfma_f32_16x16x32_bf16 v[56:59], v[150:153], v[162:165], v[56:59]
	v_mfma_f32_16x16x32_bf16 v[52:55], v[132:135], v[176:179], v[52:55]
	v_mfma_f32_16x16x32_bf16 v[40:43], v[150:153], v[176:179], v[40:43]
	v_mfma_f32_16x16x32_bf16 v[36:39], v[132:135], v[184:187], v[36:39]
	v_mfma_f32_16x16x32_bf16 v[24:27], v[150:153], v[184:187], v[24:27]
	v_mfma_f32_16x16x32_bf16 v[20:23], v[132:135], v[192:195], v[20:23]
	v_mfma_f32_16x16x32_bf16 v[8:11], v[150:153], v[192:195], v[8:11]

	s_barrier
	s_add_u32 s18, s18, 0x160080
	s_addc_u32 s19, s19, 0
	s_add_i32 s20, s20, s25
	s_mov_b32 m0, s20
	s_add_u32 s16, s16, 0x100
	s_addc_u32 s17, s17, 0

	global_load_lds_dwordx4 v140, s[18:19]
	s_add_i32 m0, s20, 0x2000
	s_add_u32 s52, s52, 0x100
	s_addc_u32 s53, s53, 0

	global_load_lds_dwordx4 v142, s[18:19]
	s_waitcnt vmcnt(6)
	s_barrier

	v_mfma_f32_16x16x32_bf16 v[48:51], v[196:199], v[154:157], v[48:51]
	v_mfma_f32_16x16x32_bf16 v[44:47], v[204:207], v[154:157], v[44:47]
	v_mfma_f32_16x16x32_bf16 v[32:35], v[196:199], v[172:175], v[32:35]
	v_mfma_f32_16x16x32_bf16 v[28:31], v[204:207], v[172:175], v[28:31]
	v_mfma_f32_16x16x32_bf16 v[16:19], v[196:199], v[180:183], v[16:19]
	v_mfma_f32_16x16x32_bf16 v[12:15], v[204:207], v[180:183], v[12:15]
	v_mfma_f32_16x16x32_bf16 v[4:7], v[196:199], v[188:191], v[4:7]
	v_mfma_f32_16x16x32_bf16 v[0:3], v[204:207], v[188:191], v[0:3]
	v_mfma_f32_16x16x32_bf16 v[48:51], v[200:203], v[162:165], v[48:51]
	v_mfma_f32_16x16x32_bf16 v[44:47], v[212:215], v[162:165], v[44:47]
	v_mfma_f32_16x16x32_bf16 v[32:35], v[200:203], v[176:179], v[32:35]
	v_mfma_f32_16x16x32_bf16 v[28:31], v[212:215], v[176:179], v[28:31]
	v_mfma_f32_16x16x32_bf16 v[16:19], v[200:203], v[184:187], v[16:19]
	v_mfma_f32_16x16x32_bf16 v[12:15], v[212:215], v[184:187], v[12:15]
	v_mfma_f32_16x16x32_bf16 v[4:7], v[200:203], v[192:195], v[4:7]
	v_mfma_f32_16x16x32_bf16 v[0:3], v[212:215], v[192:195], v[0:3]


	s_cmp_ge_i32 s54, s51
	s_mov_b32 s18, s54
	s_barrier
	s_cbranch_scc0 .LBB0_1258
	v_mov_b32_e32 v128, v210
	v_mov_b32_e32 v129, v169
	s_mov_b64 s[16:17], -1
	v_lshl_add_u32 v128, v128, 4, v129
	v_ashrrev_i32_e32 v150, 2, v128
	v_and_b32_e32 v129, 3, v129
	v_and_b32_e32 v128, -4, v128
	v_lshl_add_u32 v162, v129, 6, v128
	s_cmp_lt_i32 s2, 0
	v_lshlrev_b32_e32 v144, 4, v129
	s_cbranch_scc0 .LBB0_1261
	s_lshl_b32 s13, s50, 8
	s_add_i32 s13, s13, s30
	v_add_u32_e32 v128, s13, v150
	v_ashrrev_i32_e32 v129, 31, v128
	v_readlane_b32 s52, v254, 22
	v_lshlrev_b64 v[128:129], 13, v[128:129]
	v_readlane_b32 s66, v254, 36
	v_readlane_b32 s67, v254, 37
	s_lshl_b32 s16, s49, 8
	s_ashr_i32 s17, s16, 31
	v_lshl_add_u64 v[128:129], s[66:67], 0, v[128:129]
	v_lshl_add_u64 v[128:129], s[16:17], 2, v[128:129]
	s_lshl_b32 s16, s31, 2
	s_mov_b32 s17, s3
	v_lshl_add_u64 v[128:129], v[128:129], 0, s[16:17]
	v_lshl_add_u64 v[152:153], v[128:129], 0, v[144:145]
	global_load_dwordx4 v[164:167], v[152:153], off
	global_load_dwordx4 v[172:175], v[152:153], off offset:64
	global_load_dwordx4 v[176:179], v[152:153], off offset:512
	global_load_dwordx4 v[180:183], v[152:153], off offset:576
	v_add_co_u32_e32 v136, vcc, s37, v152
	ds_bpermute_b32 v138, v162, v124
	s_nop 0
	v_addc_co_u32_e32 v137, vcc, 0, v153, vcc
	global_load_dwordx4 v[184:187], v[136:137], off
	global_load_dwordx4 v[188:191], v[136:137], off offset:64
	global_load_dwordx4 v[192:195], v[136:137], off offset:512
	global_load_dwordx4 v[132:135], v[136:137], off offset:576
	v_add_co_u32_e32 v208, vcc, s38, v152
	ds_bpermute_b32 v139, v162, v125
	s_nop 0
	v_addc_co_u32_e32 v209, vcc, 0, v153, vcc
	global_load_dwordx4 v[196:199], v[208:209], off
	global_load_dwordx4 v[200:203], v[208:209], off offset:64
	global_load_dwordx4 v[204:207], v[208:209], off offset:512
	global_load_dwordx4 v[212:215], v[208:209], off offset:576
	v_add_co_u32_e32 v154, vcc, s39, v152
	ds_bpermute_b32 v156, v162, v126
	s_nop 0
	v_addc_co_u32_e32 v155, vcc, 0, v153, vcc
	global_load_dwordx4 v[216:219], v[154:155], off
	global_load_dwordx4 v[220:223], v[154:155], off offset:64
	global_load_dwordx4 v[224:227], v[154:155], off offset:512
	global_load_dwordx4 v[128:131], v[154:155], off offset:576
	ds_bpermute_b32 v157, v162, v127
	ds_bpermute_b32 v228, v162, v120
	ds_bpermute_b32 v229, v162, v121
	ds_bpermute_b32 v230, v162, v122
	ds_bpermute_b32 v231, v162, v123
	ds_bpermute_b32 v232, v162, v112
	ds_bpermute_b32 v233, v162, v113
	ds_bpermute_b32 v234, v162, v114
	ds_bpermute_b32 v235, v162, v115
	ds_bpermute_b32 v236, v162, v108
	ds_bpermute_b32 v237, v162, v109
	ds_bpermute_b32 v238, v162, v110
	ds_bpermute_b32 v239, v162, v111
	ds_bpermute_b32 v240, v162, v116
	ds_bpermute_b32 v241, v162, v117
	ds_bpermute_b32 v242, v162, v118
	ds_bpermute_b32 v243, v162, v119
	ds_bpermute_b32 v244, v162, v104
	ds_bpermute_b32 v245, v162, v105
	ds_bpermute_b32 v246, v162, v106
	ds_bpermute_b32 v247, v162, v107
	ds_bpermute_b32 v248, v162, v100
	ds_bpermute_b32 v249, v162, v101
	ds_bpermute_b32 v250, v162, v102
	ds_bpermute_b32 v251, v162, v103
	ds_bpermute_b32 v252, v162, v94
	ds_bpermute_b32 v253, v162, v95
	v_readlane_b32 s53, v254, 23
	v_readlane_b32 s54, v254, 24
	v_readlane_b32 s55, v254, 25
	v_readlane_b32 s56, v254, 26
	v_readlane_b32 s57, v254, 27
	v_readlane_b32 s58, v254, 28
	v_readlane_b32 s59, v254, 29
	v_readlane_b32 s60, v254, 30
	v_readlane_b32 s61, v254, 31
	v_readlane_b32 s62, v254, 32
	v_readlane_b32 s63, v254, 33
	v_readlane_b32 s64, v254, 34
	v_readlane_b32 s65, v254, 35
	s_mov_b64 s[16:17], 0
	s_waitcnt vmcnt(0) lgkmcnt(0)
	v_pk_add_f32 v[164:165], v[164:165], v[138:139]
	ds_bpermute_b32 v138, v162, v92
	ds_bpermute_b32 v139, v162, v93
	v_pk_add_f32 v[166:167], v[166:167], v[156:157]
	v_pk_add_f32 v[172:173], v[172:173], v[228:229]
	v_pk_add_f32 v[174:175], v[174:175], v[230:231]
	v_pk_add_f32 v[178:179], v[178:179], v[234:235]
	v_pk_add_f32 v[176:177], v[176:177], v[232:233]
	v_pk_add_f32 v[182:183], v[182:183], v[238:239]
	v_pk_add_f32 v[180:181], v[180:181], v[236:237]
	global_store_dwordx4 v[152:153], v[164:167], off
	global_store_dwordx4 v[152:153], v[172:175], off offset:64
	global_store_dwordx4 v[152:153], v[176:179], off offset:512
	global_store_dwordx4 v[152:153], v[180:183], off offset:576
	v_pk_add_f32 v[166:167], v[186:187], v[242:243]
	v_pk_add_f32 v[164:165], v[184:185], v[240:241]
	v_pk_add_f32 v[172:173], v[188:189], v[244:245]
	v_add_co_u32_e32 v156, vcc, s40, v152
	v_pk_add_f32 v[174:175], v[190:191], v[246:247]
	v_pk_add_f32 v[178:179], v[194:195], v[250:251]
	v_pk_add_f32 v[176:177], v[192:193], v[248:249]
	global_store_dwordx4 v[136:137], v[164:167], off
	global_store_dwordx4 v[136:137], v[172:175], off offset:64
	global_store_dwordx4 v[136:137], v[176:179], off offset:512
	v_addc_co_u32_e32 v157, vcc, 0, v153, vcc
	ds_bpermute_b32 v172, v162, v98
	ds_bpermute_b32 v173, v162, v99
	v_pk_add_f32 v[134:135], v[134:135], v[252:253]
	global_load_dwordx4 v[164:167], v[156:157], off
	s_waitcnt lgkmcnt(2)
	v_pk_add_f32 v[132:133], v[132:133], v[138:139]
	global_store_dwordx4 v[136:137], v[132:135], off offset:576
	ds_bpermute_b32 v132, v162, v96
	ds_bpermute_b32 v133, v162, v97
	ds_bpermute_b32 v136, v162, v90
	ds_bpermute_b32 v137, v162, v91
	ds_bpermute_b32 v138, v162, v88
	ds_bpermute_b32 v139, v162, v89
	s_waitcnt lgkmcnt(6)
	v_pk_add_f32 v[134:135], v[198:199], v[172:173]
	global_load_dwordx4 v[172:175], v[156:157], off offset:64
	s_waitcnt lgkmcnt(4)
	v_pk_add_f32 v[132:133], v[196:197], v[132:133]
	global_store_dwordx4 v[208:209], v[132:135], off
	ds_bpermute_b32 v180, v162, v76
	ds_bpermute_b32 v182, v162, v78
	s_waitcnt lgkmcnt(4)
	v_pk_add_f32 v[134:135], v[202:203], v[136:137]
	ds_bpermute_b32 v136, v162, v86
	ds_bpermute_b32 v137, v162, v87
	s_waitcnt lgkmcnt(4)
	v_pk_add_f32 v[132:133], v[200:201], v[138:139]
	ds_bpermute_b32 v138, v162, v84
	ds_bpermute_b32 v139, v162, v85
	global_store_dwordx4 v[208:209], v[132:135], off offset:64
	global_load_dwordx4 v[132:135], v[156:157], off offset:512
	s_waitcnt lgkmcnt(2)
	v_pk_add_f32 v[178:179], v[206:207], v[136:137]
	ds_bpermute_b32 v183, v162, v79
	s_waitcnt lgkmcnt(1)
	v_pk_add_f32 v[176:177], v[204:205], v[138:139]
	global_load_dwordx4 v[136:139], v[156:157], off offset:576
	ds_bpermute_b32 v181, v162, v77
	global_store_dwordx4 v[208:209], v[176:179], off offset:512
	v_add_co_u32_e32 v204, vcc, s41, v152
	s_waitcnt lgkmcnt(1)
	v_pk_add_f32 v[178:179], v[214:215], v[182:183]
	s_waitcnt lgkmcnt(0)
	v_pk_add_f32 v[176:177], v[212:213], v[180:181]
	ds_bpermute_b32 v180, v162, v80
	ds_bpermute_b32 v181, v162, v81
	ds_bpermute_b32 v182, v162, v82
	ds_bpermute_b32 v183, v162, v83
	v_addc_co_u32_e32 v205, vcc, 0, v153, vcc
	global_store_dwordx4 v[208:209], v[176:179], off offset:576
	global_load_dwordx4 v[176:179], v[204:205], off
	s_waitcnt lgkmcnt(0)
	v_pk_add_f32 v[182:183], v[218:219], v[182:183]
	global_load_dwordx4 v[184:187], v[204:205], off offset:64
	v_pk_add_f32 v[180:181], v[216:217], v[180:181]
	ds_bpermute_b32 v188, v162, v74
	ds_bpermute_b32 v189, v162, v75
	global_store_dwordx4 v[154:155], v[180:183], off
	ds_bpermute_b32 v180, v162, v72
	ds_bpermute_b32 v181, v162, v73
	ds_bpermute_b32 v192, v162, v68
	s_waitcnt lgkmcnt(3)
	v_pk_add_f32 v[182:183], v[222:223], v[188:189]
	global_load_dwordx4 v[188:191], v[204:205], off offset:512
	ds_bpermute_b32 v193, v162, v69
	s_waitcnt lgkmcnt(2)
	v_pk_add_f32 v[180:181], v[220:221], v[180:181]
	ds_bpermute_b32 v194, v162, v70
	ds_bpermute_b32 v195, v162, v71
	global_store_dwordx4 v[154:155], v[180:183], off offset:64
	global_load_dwordx4 v[180:183], v[204:205], off offset:576
	ds_bpermute_b32 v200, v162, v64
	ds_bpermute_b32 v196, v162, v66
	ds_bpermute_b32 v197, v162, v67
	ds_bpermute_b32 v201, v162, v65
	v_add_co_u32_e32 v206, vcc, s42, v152
	s_waitcnt lgkmcnt(4)
	v_pk_add_f32 v[194:195], v[226:227], v[194:195]
	v_pk_add_f32 v[192:193], v[224:225], v[192:193]
	v_addc_co_u32_e32 v207, vcc, 0, v153, vcc
	global_store_dwordx4 v[154:155], v[192:195], off offset:512
	global_load_dwordx4 v[192:195], v[206:207], off
	s_waitcnt lgkmcnt(1)
	v_pk_add_f32 v[130:131], v[130:131], v[196:197]
	s_waitcnt lgkmcnt(0)
	v_pk_add_f32 v[128:129], v[128:129], v[200:201]
	global_load_dwordx4 v[196:199], v[206:207], off offset:64
	ds_bpermute_b32 v202, v162, v62
	ds_bpermute_b32 v203, v162, v63
	global_store_dwordx4 v[154:155], v[128:131], off offset:576
	ds_bpermute_b32 v128, v162, v60
	ds_bpermute_b32 v129, v162, v61
	ds_bpermute_b32 v208, v162, v58
	ds_bpermute_b32 v209, v162, v59
	s_waitcnt vmcnt(18) lgkmcnt(4)
	v_pk_add_f32 v[130:131], v[166:167], v[202:203]
	ds_bpermute_b32 v154, v162, v56
	global_load_dwordx4 v[200:203], v[206:207], off offset:512
	ds_bpermute_b32 v155, v162, v57
	s_waitcnt lgkmcnt(4)
	v_pk_add_f32 v[128:129], v[164:165], v[128:129]
	global_load_dwordx4 v[164:167], v[206:207], off offset:576
	ds_bpermute_b32 v212, v162, v44
	global_store_dwordx4 v[156:157], v[128:131], off
	ds_bpermute_b32 v214, v162, v46
	ds_bpermute_b32 v215, v162, v47
	s_waitcnt vmcnt(19) lgkmcnt(5)
	v_pk_add_f32 v[130:131], v[174:175], v[208:209]
	v_add_co_u32_e32 v208, vcc, s43, v152
	s_waitcnt lgkmcnt(3)
	v_pk_add_f32 v[128:129], v[172:173], v[154:155]
	v_addc_co_u32_e32 v209, vcc, 0, v153, vcc
	global_store_dwordx4 v[156:157], v[128:131], off offset:64
	ds_bpermute_b32 v172, v162, v48
	ds_bpermute_b32 v173, v162, v49
	global_load_dwordx4 v[128:131], v[208:209], off
	global_load_dwordx4 v[152:155], v[208:209], off offset:64
	ds_bpermute_b32 v174, v162, v50
	ds_bpermute_b32 v175, v162, v51
	ds_bpermute_b32 v213, v162, v45
	s_waitcnt vmcnt(19) lgkmcnt(3)
	v_pk_add_f32 v[132:133], v[132:133], v[172:173]
	ds_bpermute_b32 v172, v162, v54
	ds_bpermute_b32 v173, v162, v55
	s_waitcnt lgkmcnt(3)
	v_pk_add_f32 v[134:135], v[134:135], v[174:175]
	global_store_dwordx4 v[156:157], v[132:135], off offset:512
	s_waitcnt vmcnt(16) lgkmcnt(0)
	v_pk_add_f32 v[174:175], v[178:179], v[172:173]
	v_pk_add_f32 v[134:135], v[138:139], v[214:215]
	v_pk_add_f32 v[132:133], v[136:137], v[212:213]
	global_store_dwordx4 v[156:157], v[132:135], off offset:576
	global_load_dwordx4 v[132:135], v[208:209], off offset:512
	ds_bpermute_b32 v156, v162, v52
	global_load_dwordx4 v[136:139], v[208:209], off offset:576
	ds_bpermute_b32 v157, v162, v53
	ds_bpermute_b32 v212, v162, v40
	ds_bpermute_b32 v214, v162, v42
	ds_bpermute_b32 v215, v162, v43
	ds_bpermute_b32 v213, v162, v41
	s_waitcnt lgkmcnt(4)
	v_pk_add_f32 v[172:173], v[176:177], v[156:157]
	global_store_dwordx4 v[204:205], v[172:175], off
	ds_bpermute_b32 v156, v162, v32
	ds_bpermute_b32 v157, v162, v33
	s_waitcnt vmcnt(19) lgkmcnt(3)
	v_pk_add_f32 v[174:175], v[186:187], v[214:215]
	s_waitcnt lgkmcnt(2)
	v_pk_add_f32 v[172:173], v[184:185], v[212:213]
	global_store_dwordx4 v[204:205], v[172:175], off offset:64
	ds_bpermute_b32 v172, v162, v34
	ds_bpermute_b32 v173, v162, v35
	ds_bpermute_b32 v176, v162, v28
	ds_bpermute_b32 v178, v162, v30
	ds_bpermute_b32 v179, v162, v31
	ds_bpermute_b32 v177, v162, v29
	s_waitcnt vmcnt(18) lgkmcnt(4)
	v_pk_add_f32 v[174:175], v[190:191], v[172:173]
	v_pk_add_f32 v[172:173], v[188:189], v[156:157]
	global_store_dwordx4 v[204:205], v[172:175], off offset:512
	ds_bpermute_b32 v156, v162, v36
	ds_bpermute_b32 v157, v162, v37
	s_waitcnt vmcnt(17) lgkmcnt(3)
	v_pk_add_f32 v[174:175], v[182:183], v[178:179]
	s_waitcnt lgkmcnt(2)
	v_pk_add_f32 v[172:173], v[180:181], v[176:177]
	global_store_dwordx4 v[204:205], v[172:175], off offset:576
	ds_bpermute_b32 v172, v162, v38
	ds_bpermute_b32 v173, v162, v39
	ds_bpermute_b32 v176, v162, v24
	ds_bpermute_b32 v178, v162, v26
	ds_bpermute_b32 v179, v162, v27
	ds_bpermute_b32 v177, v162, v25
	s_waitcnt vmcnt(16) lgkmcnt(4)
	v_pk_add_f32 v[174:175], v[194:195], v[172:173]
	v_pk_add_f32 v[172:173], v[192:193], v[156:157]
	global_store_dwordx4 v[206:207], v[172:175], off
	ds_bpermute_b32 v156, v162, v16
	ds_bpermute_b32 v157, v162, v17
	s_waitcnt vmcnt(16) lgkmcnt(3)
	v_pk_add_f32 v[174:175], v[198:199], v[178:179]
	s_waitcnt lgkmcnt(2)
	v_pk_add_f32 v[172:173], v[196:197], v[176:177]
	ds_bpermute_b32 v176, v162, v12
	ds_bpermute_b32 v178, v162, v14
	ds_bpermute_b32 v179, v162, v15
	ds_bpermute_b32 v177, v162, v13
	global_store_dwordx4 v[206:207], v[172:175], off offset:64
	ds_bpermute_b32 v172, v162, v18
	ds_bpermute_b32 v173, v162, v19
	s_waitcnt vmcnt(14) lgkmcnt(3)
	v_pk_add_f32 v[166:167], v[166:167], v[178:179]
	s_waitcnt lgkmcnt(2)
	v_pk_add_f32 v[164:165], v[164:165], v[176:177]
	global_store_dwordx4 v[206:207], v[164:167], off offset:576
	ds_bpermute_b32 v164, v162, v22
	s_waitcnt lgkmcnt(1)
	v_pk_add_f32 v[174:175], v[202:203], v[172:173]
	v_pk_add_f32 v[172:173], v[200:201], v[156:157]
	ds_bpermute_b32 v156, v162, v20
	ds_bpermute_b32 v157, v162, v21
	ds_bpermute_b32 v165, v162, v23
	global_store_dwordx4 v[206:207], v[172:175], off offset:512
	ds_bpermute_b32 v166, v162, v8
	ds_bpermute_b32 v172, v162, v10
	ds_bpermute_b32 v173, v162, v11
	ds_bpermute_b32 v167, v162, v9
	s_waitcnt vmcnt(13) lgkmcnt(4)
	v_pk_add_f32 v[130:131], v[130:131], v[164:165]
	v_pk_add_f32 v[128:129], v[128:129], v[156:157]
	global_store_dwordx4 v[208:209], v[128:131], off
	s_waitcnt vmcnt(13) lgkmcnt(1)
	s_nop 0
	v_pk_add_f32 v[130:131], v[154:155], v[172:173]
	s_waitcnt lgkmcnt(0)
	v_pk_add_f32 v[128:129], v[152:153], v[166:167]
	global_store_dwordx4 v[208:209], v[128:131], off offset:64
	ds_bpermute_b32 v128, v162, v4
	ds_bpermute_b32 v129, v162, v5
	ds_bpermute_b32 v130, v162, v6
	ds_bpermute_b32 v131, v162, v7
	ds_bpermute_b32 v152, v162, v0
	ds_bpermute_b32 v154, v162, v2
	ds_bpermute_b32 v155, v162, v3
	ds_bpermute_b32 v153, v162, v1
	s_waitcnt vmcnt(11) lgkmcnt(4)
	v_pk_add_f32 v[130:131], v[134:135], v[130:131]
	v_pk_add_f32 v[128:129], v[132:133], v[128:129]
	global_store_dwordx4 v[208:209], v[128:131], off offset:512
	s_waitcnt vmcnt(11) lgkmcnt(1)
	s_nop 0
	v_pk_add_f32 v[130:131], v[138:139], v[154:155]
	s_waitcnt lgkmcnt(0)
	v_pk_add_f32 v[128:129], v[136:137], v[152:153]
	global_store_dwordx4 v[208:209], v[128:131], off offset:576
